# HGRN chunk phases: counted vmcnt at the prefetch join instead of vmcnt(0), so the next unit's input loads stay in flight for most of the unit (waitcnt placement lever)
# speedup vs baseline: 1.0099x; 1.0099x over previous
; DI unsigned f2bf(float f) { unsigned u = __builtin_bit_cast(unsigned, f); return (u + 0x7fffu + ((u >> 16) & 1u)) >> 16; }
; #define MFMA32(a, b, c) __builtin_amdgcn_mfma_f32_32x32x16_bf16((a), (b), (c), 0, 0, 0)
; template <int MODE> DI void hgrn_chunk_phase(const Args& A, int wave_s, int l, bool need_ctx, LAS unsigned char* lds) {
;     ...
;         if (MODE == 0) {
;             const int kblk = (wave >> 1) & 1, dvblk = wave & 1;
;             f32x16 S;
; #pragma unroll
;             for (int i = 0; i < 16; ++i) S[i] = 0.f;
; #pragma unroll
;             for (int is = 0; is < 4; ++is) { const bf16x8 a = tr_nat(img, 16 * is, 32 * kblk, lane), bb = tr_nat(img + HG_IMG, 16 * is, 32 * dvblk, lane); S = MFMA32(a, bb, S); }
; #pragma unroll
;             for (int i = 0; i < 16; ++i) { const int k = 32 * kblk + (i & 3) + 8 * (i >> 2) + 4 * h5; SL[k * 64 + 32 * dvblk + r] = (bf16)f2bf(S[i]); }
.LBB0_241:
	s_or_b64 exec, exec, s[26:27]
	s_waitcnt vmcnt(0)
	s_waitcnt lgkmcnt(0)
	s_barrier
	ds_read_b64_tr_b16 v[0:1], v63
	ds_read_b64_tr_b16 v[2:3], v63 offset:576
	ds_read_b64_tr_b16 v[4:5], v64 offset:9216
	ds_read_b64_tr_b16 v[6:7], v64 offset:9792
	ds_read_b64_tr_b16 v[50:51], v63 offset:2304
	ds_read_b64_tr_b16 v[52:53], v63 offset:2880
	ds_read_b64_tr_b16 v[82:83], v64 offset:11520
	ds_read_b64_tr_b16 v[84:85], v64 offset:12096
	s_waitcnt lgkmcnt(4)
	v_mfma_f32_32x32x16_bf16 v[0:15], v[0:3], v[4:7], 0
	s_ashr_i32 s23, s22, 31
	s_lshl_b64 s[22:23], s[22:23], 13
	v_readlane_b32 s26, v253, 26
	v_readlane_b32 s27, v253, 27
	s_add_u32 s22, s26, s22
	s_addc_u32 s23, s27, s23
	s_sub_i32 s29, s29, s90
	s_waitcnt lgkmcnt(0)
	v_mfma_f32_32x32x16_bf16 v[0:15], v[50:53], v[82:85], v[0:15]
	ds_read_b64_tr_b16 v[50:51], v63 offset:4608
	ds_read_b64_tr_b16 v[52:53], v63 offset:5184
	ds_read_b64_tr_b16 v[82:83], v64 offset:13824
	ds_read_b64_tr_b16 v[84:85], v64 offset:14400
	v_add_u32_e32 v55, s28, v55
	v_add_u32_e32 v59, s28, v59
	s_andn2_b64 vcc, exec, s[24:25]
	v_mov_b32_e32 v88, v65
	v_mov_b32_e32 v86, v67
	v_mov_b32_e32 v87, v69
	s_waitcnt lgkmcnt(0)
	v_mfma_f32_32x32x16_bf16 v[0:15], v[50:53], v[82:85], v[0:15]
	ds_read_b64_tr_b16 v[50:51], v63 offset:6912
	ds_read_b64_tr_b16 v[52:53], v63 offset:7488
	ds_read_b64_tr_b16 v[82:83], v64 offset:16128
	ds_read_b64_tr_b16 v[84:85], v64 offset:16704
	v_mov_b32_e32 v80, v81
	v_mov_b32_e32 v89, v79
	s_waitcnt lgkmcnt(0)
	v_mfma_f32_32x32x16_bf16 v[0:15], v[50:53], v[82:85], v[0:15]
	v_mov_b32_e32 v84, v72
	v_mov_b32_e32 v85, v73
	v_mov_b32_e32 v82, v75
	v_mov_b32_e32 v83, v77
	s_nop 7
	v_bfe_u32 v50, v0, 16, 1
	v_add3_u32 v0, v0, v50, s79
	v_lshl_add_u64 v[50:51], v[18:19], 1, s[22:23]
	global_store_short_d16_hi v[50:51], v0, off
	v_bfe_u32 v0, v1, 16, 1
	v_add3_u32 v50, v1, v0, s79
	v_lshl_add_u64 v[0:1], v[20:21], 1, s[22:23]
	global_store_short_d16_hi v[0:1], v50, off
	v_bfe_u32 v0, v2, 16, 1
	v_add3_u32 v2, v2, v0, s79
	v_lshl_add_u64 v[0:1], v[22:23], 1, s[22:23]
	global_store_short_d16_hi v[0:1], v2, off
	v_bfe_u32 v0, v3, 16, 1
	v_add3_u32 v2, v3, v0, s79
	v_lshl_add_u64 v[0:1], v[24:25], 1, s[22:23]
	global_store_short_d16_hi v[0:1], v2, off
	v_bfe_u32 v0, v4, 16, 1
	v_add3_u32 v2, v4, v0, s79
	v_lshl_add_u64 v[0:1], v[26:27], 1, s[22:23]
	global_store_short_d16_hi v[0:1], v2, off
	v_bfe_u32 v0, v5, 16, 1
	v_add3_u32 v2, v5, v0, s79
	v_lshl_add_u64 v[0:1], v[28:29], 1, s[22:23]
	global_store_short_d16_hi v[0:1], v2, off
	v_bfe_u32 v0, v6, 16, 1
	v_add3_u32 v2, v6, v0, s79
	v_lshl_add_u64 v[0:1], v[30:31], 1, s[22:23]
	global_store_short_d16_hi v[0:1], v2, off
	v_bfe_u32 v0, v7, 16, 1
	v_add3_u32 v2, v7, v0, s79
	v_lshl_add_u64 v[0:1], v[32:33], 1, s[22:23]
	global_store_short_d16_hi v[0:1], v2, off
	v_bfe_u32 v0, v8, 16, 1
	v_add3_u32 v2, v8, v0, s79
	v_lshl_add_u64 v[0:1], v[34:35], 1, s[22:23]
	global_store_short_d16_hi v[0:1], v2, off
	v_bfe_u32 v0, v9, 16, 1
	v_add3_u32 v2, v9, v0, s79
	v_lshl_add_u64 v[0:1], v[36:37], 1, s[22:23]
	global_store_short_d16_hi v[0:1], v2, off
	v_bfe_u32 v0, v10, 16, 1
	v_add3_u32 v2, v10, v0, s79
	v_lshl_add_u64 v[0:1], v[38:39], 1, s[22:23]
	global_store_short_d16_hi v[0:1], v2, off
	v_bfe_u32 v0, v11, 16, 1
	v_add3_u32 v2, v11, v0, s79
	v_lshl_add_u64 v[0:1], v[40:41], 1, s[22:23]
	global_store_short_d16_hi v[0:1], v2, off
	v_bfe_u32 v0, v12, 16, 1
	v_add3_u32 v2, v12, v0, s79
	v_lshl_add_u64 v[0:1], v[42:43], 1, s[22:23]
	global_store_short_d16_hi v[0:1], v2, off
	v_bfe_u32 v0, v13, 16, 1
	v_add3_u32 v2, v13, v0, s79
	v_lshl_add_u64 v[0:1], v[44:45], 1, s[22:23]
	global_store_short_d16_hi v[0:1], v2, off
	v_bfe_u32 v0, v14, 16, 1
	v_add3_u32 v2, v14, v0, s79
	v_lshl_add_u64 v[0:1], v[46:47], 1, s[22:23]
	global_store_short_d16_hi v[0:1], v2, off
	v_bfe_u32 v0, v15, 16, 1
	v_add3_u32 v2, v15, v0, s79
	v_lshl_add_u64 v[0:1], v[48:49], 1, s[22:23]
	global_store_short_d16_hi v[0:1], v2, off
	v_mov_b32_e32 v2, v66
	v_mov_b32_e32 v4, v68
	v_mov_b32_e32 v6, v70
	v_mov_b32_e32 v8, v71
	v_mov_b32_e32 v12, v74
	v_mov_b32_e32 v11, v76
	v_mov_b32_e32 v10, v78
	s_mov_b32 s22, s30
	s_cbranch_vccz .LBB0_246
; template <int MODE> DI void hgrn_chunk_phase(const Args& A, int wave_s, int l, bool need_ctx, LAS unsigned char* lds) {
;     ...
;         const float lb0 = C.SM[SM_LOWER + (l * 2 + dir) * 256 + hd * 64 + 2 * kp], lb1 = C.SM[SM_LOWER + (l * 2 + dir) * 256 + hd * 64 + 2 * kp + 1];
.LBB0_242:
	s_mul_hi_i32 s23, s22, 0x3e0f83e1
	s_lshr_b32 s24, s23, 31
	s_ashr_i32 s26, s23, 5
	s_add_i32 s26, s26, s24
	s_lshl_b32 s23, s26, 6
	s_and_b32 s23, s23, 0xc0
	v_or_b32_e32 v0, s23, v58
	v_ashrrev_i32_e32 v1, 31, v0
	v_lshl_add_u64 v[0:1], v[0:1], 2, s[92:93]
	global_load_dwordx2 v[0:1], v[0:1], off
	s_add_i32 s30, s22, s90
	s_cmpk_gt_i32 s30, 0x83f
	s_cselect_b64 s[24:25], -1, 0
	s_and_b64 vcc, exec, s[24:25]
	s_cbranch_vccnz .Lhg0_skip
	s_mul_hi_i32 s23, s30, 0x3e0f83e1
	s_lshr_b32 s27, s23, 31
	s_ashr_i32 s23, s23, 5
	s_add_i32 s23, s23, s27
	s_mul_i32 s27, s23, 0xffffff7c
	s_add_i32 s27, s30, s27
	s_ashr_i32 s31, s23, 2
	s_cmp_lt_i32 s27, 4
	s_cselect_b32 s27, 8, 13
	s_mov_b32 s33, 0x8000
	s_cselect_b32 s33, s33, 0xffffff00
	s_lshl_b32 s27, s31, s27
	s_lshl_b32 s31, s23, 6
	s_add_i32 s33, s33, s27
	s_mulk_i32 s23, 0x2100
	s_sub_i32 s23, s33, s23
	s_add_i32 s23, s23, s2
	v_add_u32_e32 v7, s23, v59
	s_and_b32 s31, s31, 0xc0
	v_add_u32_e32 v9, 63, v7
	v_add_u32_e32 v13, s23, v55
	v_or_b32_e32 v3, s31, v56
	v_cndmask_b32_e64 v9, v9, v13, s[0:1]
	v_mov_b64_e32 v[14:15], s[84:85]
	v_mad_i64_i32 v[50:51], s[34:35], v9, s77, v[14:15]
	v_lshlrev_b32_e32 v160, 1, v3
	v_or_b32_e32 v5, s31, v54
	v_lshl_add_u64 v[52:53], v[50:51], 0, v[160:161]
	global_load_dword v66, v[52:53], off
	v_lshlrev_b32_e32 v52, 1, v5
	v_mov_b32_e32 v53, v161
	v_add_u32_e32 v3, 62, v7
	v_add_u32_e32 v5, 1, v13
	v_lshl_add_u64 v[50:51], v[50:51], 0, v[52:53]
	v_cndmask_b32_e64 v3, v3, v5, s[0:1]
	global_load_dword v65, v[50:51], off offset:3584
	v_mad_i64_i32 v[50:51], s[34:35], v3, s77, v[14:15]
	v_add_u32_e32 v3, 61, v7
	v_add_u32_e32 v5, 2, v13
	v_lshl_add_u64 v[68:69], v[50:51], 0, v[160:161]
	v_lshl_add_u64 v[50:51], v[50:51], 0, v[52:53]
	v_cndmask_b32_e64 v3, v3, v5, s[0:1]
	global_load_dword v68, v[68:69], off
	v_add_u32_e32 v5, 3, v13
	global_load_dword v67, v[50:51], off offset:3584
	v_mad_i64_i32 v[50:51], s[34:35], v3, s77, v[14:15]
	v_add_u32_e32 v3, 60, v7
	v_lshl_add_u64 v[70:71], v[50:51], 0, v[160:161]
	v_lshl_add_u64 v[50:51], v[50:51], 0, v[52:53]
	v_cndmask_b32_e64 v3, v3, v5, s[0:1]
	global_load_dword v70, v[70:71], off
	v_add_u32_e32 v5, 4, v13
	global_load_dword v69, v[50:51], off offset:3584
	v_mad_i64_i32 v[50:51], s[34:35], v3, s77, v[14:15]
	v_add_u32_e32 v3, 59, v7
	v_lshl_add_u64 v[72:73], v[50:51], 0, v[160:161]
	v_lshl_add_u64 v[50:51], v[50:51], 0, v[52:53]
	v_cndmask_b32_e64 v3, v3, v5, s[0:1]
	global_load_dword v71, v[72:73], off
	v_add_u32_e32 v5, 5, v13
	global_load_dword v72, v[50:51], off offset:3584
	v_mad_i64_i32 v[50:51], s[34:35], v3, s77, v[14:15]
	v_add_u32_e32 v3, 58, v7
	v_lshl_add_u64 v[74:75], v[50:51], 0, v[160:161]
	v_lshl_add_u64 v[50:51], v[50:51], 0, v[52:53]
	v_cndmask_b32_e64 v3, v3, v5, s[0:1]
	global_load_dword v74, v[74:75], off
	v_add_u32_e32 v5, 6, v13
	global_load_dword v73, v[50:51], off offset:3584
	v_mad_i64_i32 v[50:51], s[34:35], v3, s77, v[14:15]
	v_add_u32_e32 v3, 57, v7
	v_lshl_add_u64 v[76:77], v[50:51], 0, v[160:161]
	v_lshl_add_u64 v[50:51], v[50:51], 0, v[52:53]
	v_cndmask_b32_e64 v3, v3, v5, s[0:1]
	global_load_dword v76, v[76:77], off
	v_add_u32_e32 v5, 7, v13
	global_load_dword v75, v[50:51], off offset:3584
	v_mad_i64_i32 v[50:51], s[34:35], v3, s77, v[14:15]
	v_add_u32_e32 v3, 56, v7
	v_cndmask_b32_e64 v3, v3, v5, s[0:1]
	v_lshl_add_u64 v[78:79], v[50:51], 0, v[160:161]
	v_lshl_add_u64 v[50:51], v[50:51], 0, v[52:53]
	v_mad_i64_i32 v[14:15], s[34:35], v3, s77, v[14:15]
	global_load_dword v78, v[78:79], off
	s_nop 0
	global_load_dword v77, v[50:51], off offset:3584
	v_lshl_add_u64 v[50:51], v[14:15], 0, v[160:161]
	v_lshl_add_u64 v[14:15], v[14:15], 0, v[52:53]
	global_load_dword v79, v[50:51], off
	global_load_dword v81, v[14:15], off offset:3584
	s_branch .LBB0_244

; DI float sigmoid_f(float x) { return 1.f / (1.f + __expf(-x)); }
; template <int MODE> DI void hgrn_chunk_phase(const Args& A, int wave_s, int l, bool need_ctx, LAS unsigned char* lds) {
;     ...
;         const float lb0 = C.SM[SM_LOWER + (l * 2 + dir) * 256 + hd * 64 + 2 * kp], lb1 = C.SM[SM_LOWER + (l * 2 + dir) * 256 + hd * 64 + 2 * kp + 1];
;         float cum0[8], cum1[8], kk0[8], kk1[8]; float bl0 = 0.f, bl1 = 0.f;
;         unsigned vraw[8], qraw[8], spv[8];
; #pragma unroll
;         for (int ii = 0; ii < 8; ++ii) {
;             const float pf0 = __builtin_bit_cast(float, npf[ii] << 16), pf1 = __builtin_bit_cast(float, npf[ii] & 0xffff0000u);
;             const float f0 = fmaxf(lb0 + (1.f - lb0) * sigmoid_f(pf0), 1e-30f), f1 = fmaxf(lb1 + (1.f - lb1) * sigmoid_f(pf1), 1e-30f);
;             bl0 += __logf(f0); bl1 += __logf(f1); cum0[ii] = bl0; cum1[ii] = bl1; kk0[ii] = 1.f - f0; kk1[ii] = 1.f - f1;
;             vraw[ii] = nv[ii]; qraw[ii] = nq[ii]; spv[ii] = nsp[ii]; }
;         bf16* SL = (bf16*)C.ST + ((size_t)(seq * 132 + n)) * 4096;
;         if (u + (int)gridDim.x < nunits) HG_FETCH(u + (int)gridDim.x);
;         __syncthreads();
.LBB0_244:
	v_lshlrev_b32_e32 v3, 16, v2
	v_mul_f32_e32 v3, 0xbfb8aa3b, v3
	s_mul_i32 s27, s26, 0xffffff7c
	v_exp_f32_e32 v3, v3
	s_add_i32 s27, s22, s27
	s_cmp_gt_i32 s27, 3
	s_mul_i32 s23, s26, 0x84
	s_cselect_b32 s22, 0x87, 3
	s_add_i32 s22, s22, s23
	v_add_f32_e32 v3, 1.0, v3
	s_add_i32 s31, s29, s22
	v_div_scale_f32 v5, s[22:23], v3, v3, 1.0
	v_rcp_f32_e32 v7, v5
	v_and_b32_e32 v2, 0xffff0000, v2
	v_mul_f32_e32 v2, 0xbfb8aa3b, v2
	v_exp_f32_e32 v2, v2
	v_fma_f32 v9, -v5, v7, 1.0
	v_fmac_f32_e32 v7, v9, v7
	v_div_scale_f32 v9, vcc, 1.0, v3, 1.0
	v_mul_f32_e32 v13, v9, v7
	v_fma_f32 v14, -v5, v13, v9
	v_fmac_f32_e32 v13, v14, v7
	v_fma_f32 v5, -v5, v13, v9
	v_div_fmas_f32 v5, v5, v7, v13
	s_waitcnt vmcnt(16)
	v_sub_f32_e32 v93, 1.0, v0
	v_div_fixup_f32 v3, v5, v3, 1.0
	v_fma_f32 v3, v3, v93, v0
	v_add_f32_e32 v2, 1.0, v2
	v_max_f32_e32 v5, 0xda24260, v3
	v_div_scale_f32 v3, s[22:23], v2, v2, 1.0
	v_rcp_f32_e32 v7, v3
	v_sub_f32_e32 v92, 1.0, v1
	s_and_b64 s[22:23], s[0:1], exec
	v_sub_f32_e32 v91, 1.0, v5
	v_fma_f32 v9, -v3, v7, 1.0
	v_fmac_f32_e32 v7, v9, v7
	v_div_scale_f32 v9, vcc, 1.0, v2, 1.0
	v_mul_f32_e32 v13, v9, v7
	v_fma_f32 v14, -v3, v13, v9
	v_fmac_f32_e32 v13, v14, v7
	v_fma_f32 v3, -v3, v13, v9
	v_div_fmas_f32 v3, v3, v7, v13
	v_div_fixup_f32 v2, v3, v2, 1.0
	v_fma_f32 v2, v2, v92, v1
	v_cmp_gt_f32_e32 vcc, s78, v5
	v_max_f32_e32 v7, 0xda24260, v2
	v_sub_f32_e32 v90, 1.0, v7
	v_cndmask_b32_e64 v2, 0, 32, vcc
	v_ldexp_f32 v2, v5, v2
	v_log_f32_e32 v2, v2
	v_lshlrev_b32_e32 v5, 16, v4
	v_mul_f32_e32 v5, 0xbfb8aa3b, v5
	v_exp_f32_e32 v5, v5
	v_mul_f32_e32 v3, 0x3f317217, v2
	v_fma_f32 v3, v2, s91, -v3
	v_fmac_f32_e32 v3, 0x3377d1cf, v2
	v_fmac_f32_e32 v3, 0x3f317217, v2
	v_cmp_lt_f32_e64 s[22:23], |v2|, s80
	v_add_f32_e32 v5, 1.0, v5
	v_and_b32_e32 v4, 0xffff0000, v4
	v_cndmask_b32_e64 v2, v2, v3, s[22:23]
	v_cndmask_b32_e32 v3, 0, v249, vcc
	v_cmp_gt_f32_e32 vcc, s78, v7
	v_sub_f32_e32 v2, v2, v3
	v_mul_f32_e32 v4, 0xbfb8aa3b, v4
	v_cndmask_b32_e64 v3, 0, 32, vcc
	v_ldexp_f32 v3, v7, v3
	v_log_f32_e32 v3, v3
	v_exp_f32_e32 v4, v4
	s_barrier
	v_mul_f32_e32 v9, 0x3f317217, v3
	v_fma_f32 v9, v3, s91, -v9
	v_fmac_f32_e32 v9, 0x3377d1cf, v3
	v_fmac_f32_e32 v9, 0x3f317217, v3
	v_cmp_lt_f32_e64 s[22:23], |v3|, s80
	v_add_f32_e32 v4, 1.0, v4
	s_nop 0
	v_cndmask_b32_e64 v3, v3, v9, s[22:23]
	v_cndmask_b32_e32 v9, 0, v249, vcc
	v_div_scale_f32 v7, s[22:23], v5, v5, 1.0
	v_sub_f32_e32 v3, v3, v9
	v_rcp_f32_e32 v9, v7
	s_cselect_b32 s27, s27, s31
	v_fma_f32 v13, -v7, v9, 1.0
	v_fmac_f32_e32 v9, v13, v9
	v_div_scale_f32 v13, vcc, 1.0, v5, 1.0
	v_mul_f32_e32 v14, v13, v9
	v_fma_f32 v15, -v7, v14, v13
	v_fmac_f32_e32 v14, v15, v9
	v_fma_f32 v7, -v7, v14, v13
	v_div_fmas_f32 v7, v7, v9, v14
	v_div_fixup_f32 v5, v7, v5, 1.0
	v_fma_f32 v5, v5, v93, v0
	v_max_f32_e32 v7, 0xda24260, v5
	v_div_scale_f32 v5, s[22:23], v4, v4, 1.0
	v_rcp_f32_e32 v9, v5
	v_sub_f32_e32 v95, 1.0, v7
	v_fma_f32 v13, -v5, v9, 1.0
	v_fmac_f32_e32 v9, v13, v9
	v_div_scale_f32 v13, vcc, 1.0, v4, 1.0
	v_mul_f32_e32 v14, v13, v9
	v_fma_f32 v15, -v5, v14, v13
	v_fmac_f32_e32 v14, v15, v9
	v_fma_f32 v5, -v5, v14, v13
	v_div_fmas_f32 v5, v5, v9, v14
	v_div_fixup_f32 v4, v5, v4, 1.0
	v_fma_f32 v4, v4, v92, v1
	v_cmp_gt_f32_e32 vcc, s78, v7
	v_max_f32_e32 v9, 0xda24260, v4
	v_sub_f32_e32 v94, 1.0, v9
	v_cndmask_b32_e64 v4, 0, 32, vcc
	v_ldexp_f32 v4, v7, v4
	v_log_f32_e32 v4, v4
	v_lshlrev_b32_e32 v7, 16, v6
	v_mul_f32_e32 v7, 0xbfb8aa3b, v7
	v_exp_f32_e32 v7, v7
	v_mul_f32_e32 v5, 0x3f317217, v4
	v_fma_f32 v5, v4, s91, -v5
	v_fmac_f32_e32 v5, 0x3377d1cf, v4
	v_fmac_f32_e32 v5, 0x3f317217, v4
	v_cmp_lt_f32_e64 s[22:23], |v4|, s80
	v_add_f32_e32 v7, 1.0, v7
	v_and_b32_e32 v6, 0xffff0000, v6
	v_cndmask_b32_e64 v4, v4, v5, s[22:23]
	v_cndmask_b32_e32 v5, 0, v249, vcc
	v_cmp_gt_f32_e32 vcc, s78, v9
	v_sub_f32_e32 v4, v4, v5
	v_mul_f32_e32 v6, 0xbfb8aa3b, v6
	v_cndmask_b32_e64 v5, 0, 32, vcc
	v_ldexp_f32 v5, v9, v5
	v_log_f32_e32 v5, v5
	v_exp_f32_e32 v6, v6
	v_mul_f32_e32 v13, 0x3f317217, v5
	v_fma_f32 v13, v5, s91, -v13
	v_fmac_f32_e32 v13, 0x3377d1cf, v5
	v_fmac_f32_e32 v13, 0x3f317217, v5
	v_cmp_lt_f32_e64 s[22:23], |v5|, s80
	v_add_f32_e32 v6, 1.0, v6
	s_nop 0
	v_cndmask_b32_e64 v5, v5, v13, s[22:23]
	v_cndmask_b32_e32 v13, 0, v249, vcc
	v_div_scale_f32 v9, s[22:23], v7, v7, 1.0
	v_sub_f32_e32 v5, v5, v13
	v_rcp_f32_e32 v13, v9
	s_nop 0
	v_fma_f32 v14, -v9, v13, 1.0
	v_fmac_f32_e32 v13, v14, v13
	v_div_scale_f32 v14, vcc, 1.0, v7, 1.0
	v_mul_f32_e32 v15, v14, v13
	v_fma_f32 v50, -v9, v15, v14
	v_fmac_f32_e32 v15, v50, v13
	v_fma_f32 v9, -v9, v15, v14
	v_div_fmas_f32 v9, v9, v13, v15
	v_div_fixup_f32 v7, v9, v7, 1.0
	v_fma_f32 v7, v7, v93, v0
	v_max_f32_e32 v9, 0xda24260, v7
	v_div_scale_f32 v7, s[22:23], v6, v6, 1.0
	v_rcp_f32_e32 v13, v7
	v_sub_f32_e32 v97, 1.0, v9
	v_fma_f32 v14, -v7, v13, 1.0
	v_fmac_f32_e32 v13, v14, v13
	v_div_scale_f32 v14, vcc, 1.0, v6, 1.0
	v_mul_f32_e32 v15, v14, v13
	v_fma_f32 v50, -v7, v15, v14
	v_fmac_f32_e32 v15, v50, v13
	v_fma_f32 v7, -v7, v15, v14
	v_div_fmas_f32 v7, v7, v13, v15
	v_div_fixup_f32 v6, v7, v6, 1.0
	v_fma_f32 v6, v6, v92, v1
	v_cmp_gt_f32_e32 vcc, s78, v9
	v_max_f32_e32 v13, 0xda24260, v6
	v_sub_f32_e32 v96, 1.0, v13
	v_cndmask_b32_e64 v6, 0, 32, vcc
	v_ldexp_f32 v6, v9, v6
	v_log_f32_e32 v6, v6
	v_lshlrev_b32_e32 v9, 16, v8
	v_mul_f32_e32 v9, 0xbfb8aa3b, v9
	v_exp_f32_e32 v9, v9
	v_mul_f32_e32 v7, 0x3f317217, v6
	v_fma_f32 v7, v6, s91, -v7
	v_fmac_f32_e32 v7, 0x3377d1cf, v6
	v_fmac_f32_e32 v7, 0x3f317217, v6
	v_cmp_lt_f32_e64 s[22:23], |v6|, s80
	v_add_f32_e32 v9, 1.0, v9
	v_and_b32_e32 v8, 0xffff0000, v8
	v_cndmask_b32_e64 v6, v6, v7, s[22:23]
; DI float sigmoid_f(float x) { return 1.f / (1.f + __expf(-x)); }
; template <int MODE> DI void hgrn_chunk_phase(const Args& A, int wave_s, int l, bool need_ctx, LAS unsigned char* lds) {
;     ...
;         for (int ii = 0; ii < 8; ++ii) {
;             const float pf0 = __builtin_bit_cast(float, npf[ii] << 16), pf1 = __builtin_bit_cast(float, npf[ii] & 0xffff0000u);
;             const float f0 = fmaxf(lb0 + (1.f - lb0) * sigmoid_f(pf0), 1e-30f), f1 = fmaxf(lb1 + (1.f - lb1) * sigmoid_f(pf1), 1e-30f);
;             bl0 += __logf(f0); bl1 += __logf(f1); cum0[ii] = bl0; cum1[ii] = bl1; kk0[ii] = 1.f - f0; kk1[ii] = 1.f - f1;
;             vraw[ii] = nv[ii]; qraw[ii] = nq[ii]; spv[ii] = nsp[ii]; }
	v_cndmask_b32_e32 v7, 0, v249, vcc
	v_cmp_gt_f32_e32 vcc, s78, v13
	v_sub_f32_e32 v6, v6, v7
	v_mul_f32_e32 v8, 0xbfb8aa3b, v8
	v_cndmask_b32_e64 v7, 0, 32, vcc
	v_ldexp_f32 v7, v13, v7
	v_log_f32_e32 v7, v7
	v_exp_f32_e32 v8, v8
	v_mul_f32_e32 v14, 0x3f317217, v7
	v_fma_f32 v14, v7, s91, -v14
	v_fmac_f32_e32 v14, 0x3377d1cf, v7
	v_fmac_f32_e32 v14, 0x3f317217, v7
	v_cmp_lt_f32_e64 s[22:23], |v7|, s80
	v_add_f32_e32 v8, 1.0, v8
	s_nop 0
	v_cndmask_b32_e64 v7, v7, v14, s[22:23]
	v_cndmask_b32_e32 v14, 0, v249, vcc
	v_div_scale_f32 v13, s[22:23], v9, v9, 1.0
	v_sub_f32_e32 v7, v7, v14
	v_rcp_f32_e32 v14, v13
	s_nop 0
	v_fma_f32 v15, -v13, v14, 1.0
	v_fmac_f32_e32 v14, v15, v14
	v_div_scale_f32 v15, vcc, 1.0, v9, 1.0
	v_mul_f32_e32 v50, v15, v14
	v_fma_f32 v51, -v13, v50, v15
	v_fmac_f32_e32 v50, v51, v14
	v_fma_f32 v13, -v13, v50, v15
	v_div_fmas_f32 v13, v13, v14, v50
	v_div_fixup_f32 v9, v13, v9, 1.0
	v_fma_f32 v9, v9, v93, v0
	v_max_f32_e32 v13, 0xda24260, v9
	v_div_scale_f32 v9, s[22:23], v8, v8, 1.0
	v_rcp_f32_e32 v14, v9
	v_sub_f32_e32 v99, 1.0, v13
	v_fma_f32 v15, -v9, v14, 1.0
	v_fmac_f32_e32 v14, v15, v14
	v_div_scale_f32 v15, vcc, 1.0, v8, 1.0
	v_mul_f32_e32 v50, v15, v14
	v_fma_f32 v51, -v9, v50, v15
	v_fmac_f32_e32 v50, v51, v14
	v_fma_f32 v9, -v9, v50, v15
	v_div_fmas_f32 v9, v9, v14, v50
	v_div_fixup_f32 v8, v9, v8, 1.0
	v_fma_f32 v8, v8, v92, v1
	v_cmp_gt_f32_e32 vcc, s78, v13
	v_max_f32_e32 v14, 0xda24260, v8
	v_sub_f32_e32 v98, 1.0, v14
	v_cndmask_b32_e64 v8, 0, 32, vcc
	v_ldexp_f32 v8, v13, v8
	v_log_f32_e32 v8, v8
	v_lshlrev_b32_e32 v13, 16, v12
	v_mul_f32_e32 v13, 0xbfb8aa3b, v13
	v_exp_f32_e32 v13, v13
	v_mul_f32_e32 v9, 0x3f317217, v8
	v_fma_f32 v9, v8, s91, -v9
	v_fmac_f32_e32 v9, 0x3377d1cf, v8
	v_fmac_f32_e32 v9, 0x3f317217, v8
	v_cmp_lt_f32_e64 s[22:23], |v8|, s80
	v_add_f32_e32 v13, 1.0, v13
	v_and_b32_e32 v12, 0xffff0000, v12
	v_cndmask_b32_e64 v8, v8, v9, s[22:23]
	v_cndmask_b32_e32 v9, 0, v249, vcc
	v_cmp_gt_f32_e32 vcc, s78, v14
	v_sub_f32_e32 v8, v8, v9
	v_mul_f32_e32 v12, 0xbfb8aa3b, v12
	v_cndmask_b32_e64 v9, 0, 32, vcc
	v_ldexp_f32 v9, v14, v9
	v_log_f32_e32 v9, v9
	v_exp_f32_e32 v12, v12
	v_mul_f32_e32 v15, 0x3f317217, v9
	v_fma_f32 v15, v9, s91, -v15
	v_fmac_f32_e32 v15, 0x3377d1cf, v9
	v_fmac_f32_e32 v15, 0x3f317217, v9
	v_cmp_lt_f32_e64 s[22:23], |v9|, s80
	v_add_f32_e32 v12, 1.0, v12
	s_nop 0
	v_cndmask_b32_e64 v9, v9, v15, s[22:23]
	v_cndmask_b32_e32 v15, 0, v249, vcc
	v_div_scale_f32 v14, s[22:23], v13, v13, 1.0
	v_sub_f32_e32 v9, v9, v15
	v_rcp_f32_e32 v15, v14
	s_nop 0
	v_fma_f32 v50, -v14, v15, 1.0
	v_fmac_f32_e32 v15, v50, v15
	v_div_scale_f32 v50, vcc, 1.0, v13, 1.0
	v_mul_f32_e32 v51, v50, v15
	v_fma_f32 v52, -v14, v51, v50
	v_fmac_f32_e32 v51, v52, v15
	v_fma_f32 v14, -v14, v51, v50
	v_div_fmas_f32 v14, v14, v15, v51
	v_div_fixup_f32 v13, v14, v13, 1.0
	v_fma_f32 v13, v93, v13, v0
	v_max_f32_e32 v14, 0xda24260, v13
	v_div_scale_f32 v13, s[22:23], v12, v12, 1.0
	v_rcp_f32_e32 v15, v13
	v_sub_f32_e32 v101, 1.0, v14
	v_fma_f32 v50, -v13, v15, 1.0
	v_fmac_f32_e32 v15, v50, v15
	v_div_scale_f32 v50, vcc, 1.0, v12, 1.0
	v_mul_f32_e32 v51, v50, v15
	v_fma_f32 v52, -v13, v51, v50
	v_fmac_f32_e32 v51, v52, v15
	v_fma_f32 v13, -v13, v51, v50
	v_div_fmas_f32 v13, v13, v15, v51
	v_div_fixup_f32 v12, v13, v12, 1.0
	v_fma_f32 v12, v12, v92, v1
	v_cmp_gt_f32_e32 vcc, s78, v14
	v_max_f32_e32 v15, 0xda24260, v12
	v_sub_f32_e32 v100, 1.0, v15
	v_cndmask_b32_e64 v12, 0, 32, vcc
	v_ldexp_f32 v12, v14, v12
	v_log_f32_e32 v12, v12
	v_lshlrev_b32_e32 v14, 16, v11
	v_mul_f32_e32 v14, 0xbfb8aa3b, v14
	v_exp_f32_e32 v14, v14
	v_mul_f32_e32 v13, 0x3f317217, v12
	v_fma_f32 v13, v12, s91, -v13
	v_fmac_f32_e32 v13, 0x3377d1cf, v12
	v_fmac_f32_e32 v13, 0x3f317217, v12
	v_cmp_lt_f32_e64 s[22:23], |v12|, s80
	v_add_f32_e32 v14, 1.0, v14
	v_and_b32_e32 v11, 0xffff0000, v11
	v_cndmask_b32_e64 v12, v12, v13, s[22:23]
	v_cndmask_b32_e32 v13, 0, v249, vcc
	v_cmp_gt_f32_e32 vcc, s78, v15
	v_sub_f32_e32 v12, v12, v13
	v_mul_f32_e32 v11, 0xbfb8aa3b, v11
	v_cndmask_b32_e64 v13, 0, 32, vcc
	v_ldexp_f32 v13, v15, v13
	v_log_f32_e32 v13, v13
	v_exp_f32_e32 v11, v11
	v_mul_f32_e32 v50, 0x3f317217, v13
	v_fma_f32 v50, v13, s91, -v50
	v_fmac_f32_e32 v50, 0x3377d1cf, v13
	v_fmac_f32_e32 v50, 0x3f317217, v13
	v_cmp_lt_f32_e64 s[22:23], |v13|, s80
	v_add_f32_e32 v11, 1.0, v11
	s_nop 0
	v_cndmask_b32_e64 v13, v13, v50, s[22:23]
	v_cndmask_b32_e32 v50, 0, v249, vcc
	v_div_scale_f32 v15, s[22:23], v14, v14, 1.0
	v_sub_f32_e32 v13, v13, v50
	v_rcp_f32_e32 v50, v15
	s_nop 0
	v_fma_f32 v51, -v15, v50, 1.0
	v_fmac_f32_e32 v50, v51, v50
	v_div_scale_f32 v51, vcc, 1.0, v14, 1.0
	v_mul_f32_e32 v52, v51, v50
	v_fma_f32 v53, -v15, v52, v51
	v_fmac_f32_e32 v52, v53, v50
	v_fma_f32 v15, -v15, v52, v51
	v_div_fmas_f32 v15, v15, v50, v52
	v_div_fixup_f32 v14, v15, v14, 1.0
	v_div_scale_f32 v15, s[22:23], v11, v11, 1.0
	v_rcp_f32_e32 v50, v15
	v_fma_f32 v14, v93, v14, v0
	v_max_f32_e32 v14, 0xda24260, v14
	v_sub_f32_e32 v103, 1.0, v14
	v_fma_f32 v51, -v15, v50, 1.0
	v_fmac_f32_e32 v50, v51, v50
	v_div_scale_f32 v51, vcc, 1.0, v11, 1.0
	v_mul_f32_e32 v52, v51, v50
	v_fma_f32 v53, -v15, v52, v51
	v_fmac_f32_e32 v52, v53, v50
	v_fma_f32 v15, -v15, v52, v51
	v_div_fmas_f32 v15, v15, v50, v52
	v_cmp_gt_f32_e32 vcc, s78, v14
	v_div_fixup_f32 v11, v15, v11, 1.0
	v_fma_f32 v11, v92, v11, v1
	v_cndmask_b32_e64 v15, 0, 32, vcc
	v_ldexp_f32 v15, v14, v15
	v_log_f32_e32 v15, v15
	v_max_f32_e32 v11, 0xda24260, v11
	v_sub_f32_e32 v102, 1.0, v11
	v_mul_f32_e32 v50, 0x3f317217, v15
	v_fma_f32 v50, v15, s91, -v50
	v_fmac_f32_e32 v50, 0x3377d1cf, v15
	v_fmac_f32_e32 v50, 0x3f317217, v15
; #define LAS __attribute__((address_space(3)))
; DI float sigmoid_f(float x) { return 1.f / (1.f + __expf(-x)); }
; template <int MODE> DI void hgrn_chunk_phase(const Args& A, int wave_s, int l, bool need_ctx, LAS unsigned char* lds) {
;     ...
;         for (int ii = 0; ii < 8; ++ii) {
;             const float pf0 = __builtin_bit_cast(float, npf[ii] << 16), pf1 = __builtin_bit_cast(float, npf[ii] & 0xffff0000u);
;             const float f0 = fmaxf(lb0 + (1.f - lb0) * sigmoid_f(pf0), 1e-30f), f1 = fmaxf(lb1 + (1.f - lb1) * sigmoid_f(pf1), 1e-30f);
;             bl0 += __logf(f0); bl1 += __logf(f1); cum0[ii] = bl0; cum1[ii] = bl1; kk0[ii] = 1.f - f0; kk1[ii] = 1.f - f1;
;             vraw[ii] = nv[ii]; qraw[ii] = nq[ii]; spv[ii] = nsp[ii]; }
;         bf16* SL = (bf16*)C.ST + ((size_t)(seq * 132 + n)) * 4096;
;         if (u + (int)gridDim.x < nunits) HG_FETCH(u + (int)gridDim.x);
;         __syncthreads();
;         LAS fv2* qt2 = (LAS fv2*)qt;
;         qt2[(dir * 8 + e8) * 32 + kp] = (fv2){bl0, bl1};
;         __syncthreads();
	v_cmp_lt_f32_e64 s[22:23], |v15|, s80
	s_nop 1
	v_cndmask_b32_e64 v15, v15, v50, s[22:23]
	v_cndmask_b32_e32 v50, 0, v249, vcc
	v_cmp_gt_f32_e32 vcc, s78, v11
	v_sub_f32_e32 v52, v15, v50
	s_nop 0
	v_cndmask_b32_e64 v15, 0, 32, vcc
	v_ldexp_f32 v15, v11, v15
	v_log_f32_e32 v15, v15
	v_lshlrev_b32_e32 v11, 16, v10
	v_mul_f32_e32 v11, 0xbfb8aa3b, v11
	v_exp_f32_e32 v11, v11
	v_mul_f32_e32 v50, 0x3f317217, v15
	v_fma_f32 v50, v15, s91, -v50
	v_fmac_f32_e32 v50, 0x3377d1cf, v15
	v_fmac_f32_e32 v50, 0x3f317217, v15
	v_cmp_lt_f32_e64 s[22:23], |v15|, s80
	v_add_f32_e32 v11, 1.0, v11
	v_and_b32_e32 v10, 0xffff0000, v10
	v_cndmask_b32_e64 v15, v15, v50, s[22:23]
	v_cndmask_b32_e32 v50, 0, v249, vcc
	v_div_scale_f32 v14, s[22:23], v11, v11, 1.0
	v_sub_f32_e32 v53, v15, v50
	v_rcp_f32_e32 v15, v14
	v_mul_f32_e32 v10, 0xbfb8aa3b, v10
	v_exp_f32_e32 v10, v10
	v_fma_f32 v50, -v14, v15, 1.0
	v_fmac_f32_e32 v15, v50, v15
	v_div_scale_f32 v50, vcc, 1.0, v11, 1.0
	v_mul_f32_e32 v51, v50, v15
	v_fma_f32 v104, -v14, v51, v50
	v_fmac_f32_e32 v51, v104, v15
	v_fma_f32 v14, -v14, v51, v50
	v_div_fmas_f32 v14, v14, v15, v51
	v_div_fixup_f32 v11, v14, v11, 1.0
	v_fma_f32 v11, v93, v11, v0
	v_add_f32_e32 v10, 1.0, v10
	v_max_f32_e32 v106, 0xda24260, v11
	v_div_scale_f32 v11, s[22:23], v10, v10, 1.0
	v_rcp_f32_e32 v14, v11
	s_nop 0
	v_fma_f32 v15, -v11, v14, 1.0
	v_fmac_f32_e32 v14, v15, v14
	v_div_scale_f32 v15, vcc, 1.0, v10, 1.0
	v_mul_f32_e32 v50, v15, v14
	v_fma_f32 v51, -v11, v50, v15
	v_fmac_f32_e32 v50, v51, v14
	v_fma_f32 v11, -v11, v50, v15
	v_div_fmas_f32 v11, v11, v14, v50
	v_div_fixup_f32 v10, v11, v10, 1.0
	v_fma_f32 v10, v92, v10, v1
	v_cmp_gt_f32_e32 vcc, s78, v106
	v_max_f32_e32 v107, 0xda24260, v10
	v_pk_add_f32 v[50:51], v[2:3], 0 op_sel_hi:[1,0]
	v_cndmask_b32_e64 v10, 0, 32, vcc
	v_ldexp_f32 v10, v106, v10
	v_log_f32_e32 v10, v10
	v_pk_add_f32 v[14:15], v[4:5], v[50:51]
	v_mul_f32_e32 v11, 0x3f317217, v10
	v_fma_f32 v11, v10, s91, -v11
	v_fmac_f32_e32 v11, 0x3377d1cf, v10
	v_fmac_f32_e32 v11, 0x3f317217, v10
	v_cmp_lt_f32_e64 s[22:23], |v10|, s80
	s_nop 1
	v_cndmask_b32_e64 v10, v10, v11, s[22:23]
	v_cndmask_b32_e32 v11, 0, v249, vcc
	v_cmp_gt_f32_e32 vcc, s78, v107
	v_sub_f32_e32 v104, v10, v11
	s_nop 0
	v_cndmask_b32_e64 v10, 0, 32, vcc
	v_ldexp_f32 v10, v107, v10
	v_log_f32_e32 v10, v10
	s_nop 0
	v_mul_f32_e32 v11, 0x3f317217, v10
	v_fma_f32 v11, v10, s91, -v11
	v_fmac_f32_e32 v11, 0x3377d1cf, v10
	v_fmac_f32_e32 v11, 0x3f317217, v10
	v_cmp_lt_f32_e64 s[22:23], |v10|, s80
	s_nop 1
	v_cndmask_b32_e64 v10, v10, v11, s[22:23]
	v_cndmask_b32_e32 v11, 0, v249, vcc
	v_sub_f32_e32 v105, v10, v11
	v_pk_add_f32 v[10:11], v[6:7], v[14:15]
	s_nop 0
	v_pk_add_f32 v[8:9], v[8:9], v[10:11]
	s_nop 0
	v_pk_add_f32 v[6:7], v[12:13], v[8:9]
	v_sub_f32_e32 v13, 1.0, v106
	v_pk_add_f32 v[4:5], v[52:53], v[6:7]
	v_lshlrev_b32_e32 v52, 16, v89
	v_mul_f32_e32 v52, 0xbfb8aa3b, v52
	v_exp_f32_e32 v52, v52
	v_and_b32_e32 v53, 0xffff0000, v89
	v_pk_add_f32 v[2:3], v[104:105], v[4:5]
	v_sub_f32_e32 v12, 1.0, v107
	v_add_f32_e32 v52, 1.0, v52
	v_div_scale_f32 v89, s[22:23], v52, v52, 1.0
	v_rcp_f32_e32 v104, v89
	s_nop 0
	v_fma_f32 v105, -v89, v104, 1.0
	v_fmac_f32_e32 v104, v105, v104
	v_div_scale_f32 v105, vcc, 1.0, v52, 1.0
	v_mul_f32_e32 v106, v105, v104
	v_fma_f32 v107, -v89, v106, v105
	v_fmac_f32_e32 v106, v107, v104
	v_fma_f32 v89, -v89, v106, v105
	v_div_fmas_f32 v89, v89, v104, v106
	v_div_fixup_f32 v52, v89, v52, 1.0
	v_fma_f32 v0, v93, v52, v0
	v_max_f32_e32 v52, 0xda24260, v0
	v_mul_f32_e32 v0, 0xbfb8aa3b, v53
	v_exp_f32_e32 v0, v0
	s_nop 0
	v_add_f32_e32 v0, 1.0, v0
	v_div_scale_f32 v53, s[22:23], v0, v0, 1.0
	v_rcp_f32_e32 v89, v53
	s_nop 0
	v_fma_f32 v93, -v53, v89, 1.0
	v_fmac_f32_e32 v89, v93, v89
	v_div_scale_f32 v93, vcc, 1.0, v0, 1.0
	v_mul_f32_e32 v104, v93, v89
	v_fma_f32 v105, -v53, v104, v93
	v_fmac_f32_e32 v104, v105, v89
	v_fma_f32 v53, -v53, v104, v93
	v_div_fmas_f32 v53, v53, v89, v104
	v_div_fixup_f32 v0, v53, v0, 1.0
	v_cmp_gt_f32_e32 vcc, s78, v52
	v_fmac_f32_e32 v1, v92, v0
	v_max_f32_e32 v53, 0xda24260, v1
	v_cndmask_b32_e64 v0, 0, 32, vcc
	v_ldexp_f32 v0, v52, v0
	v_log_f32_e32 v0, v0
	v_sub_f32_e32 v92, 1.0, v52
	v_sub_f32_e32 v52, 1.0, v53
	v_mul_f32_e32 v1, 0x3f317217, v0
	v_fma_f32 v1, v0, s91, -v1
	v_fmac_f32_e32 v1, 0x3377d1cf, v0
	v_fmac_f32_e32 v1, 0x3f317217, v0
	v_cmp_lt_f32_e64 s[22:23], |v0|, s80
	s_nop 1
	v_cndmask_b32_e64 v0, v0, v1, s[22:23]
	v_cndmask_b32_e32 v1, 0, v249, vcc
	v_cmp_gt_f32_e32 vcc, s78, v53
	v_sub_f32_e32 v0, v0, v1
	s_nop 0
	v_cndmask_b32_e64 v1, 0, 32, vcc
	v_ldexp_f32 v1, v53, v1
	v_log_f32_e32 v1, v1
	s_nop 0
	v_mul_f32_e32 v89, 0x3f317217, v1
	v_fma_f32 v89, v1, s91, -v89
	v_fmac_f32_e32 v89, 0x3377d1cf, v1
	v_fmac_f32_e32 v89, 0x3f317217, v1
	v_cmp_lt_f32_e64 s[22:23], |v1|, s80
	s_nop 1
	v_cndmask_b32_e64 v1, v1, v89, s[22:23]
	v_cndmask_b32_e32 v89, 0, v249, vcc
	v_sub_f32_e32 v1, v1, v89
	v_pk_add_f32 v[0:1], v[0:1], v[2:3]
	ds_write_b64 v60, v[0:1]
	s_waitcnt lgkmcnt(0)
	s_barrier
; #define LAS __attribute__((address_space(3)))
; DI unsigned pk2(float lo, float hi) { return f2bf(lo) | (f2bf(hi) << 16); }
; template <int MODE> DI void hgrn_chunk_phase(const Args& A, int wave_s, int l, bool need_ctx, LAS unsigned char* lds) {
;     ...
;         float off0 = 0.f, off1 = 0.f, bref0 = 0.f, bref1 = 0.f, bend0 = 0.f, bend1 = 0.f;
; #pragma unroll
;         for (int j = 0; j < 8; ++j) { const fv2 tq = qt2[(dir * 8 + j) * 32 + kp];
;             if (j < e8) { off0 += tq.x; off1 += tq.y; }
;             if (j < 4) { bref0 += tq.x; bref1 += tq.y; }
;             bend0 += tq.x; bend1 += tq.y; }
; #pragma unroll
;         for (int ii = 0; ii < 8; ++ii) { const int i = e8 * 8 + ii; const float bi0 = off0 + cum0[ii], bi1 = off1 + cum1[ii];
;             if (MODE == 0) {
;                 *(LAS unsigned*)(img + i * KV_PITCH + kp * 4) = pk2(kk0[ii] * __expf(bend0 - bi0), kk1[ii] * __expf(bend1 - bi1));
;                 *(LAS unsigned*)(img + HG_IMG + i * KV_PITCH + kp * 4) = vraw[ii];
;             } else {
;                 const float q0 = __builtin_bit_cast(float, qraw[ii] << 16), q1 = __builtin_bit_cast(float, qraw[ii] & 0xffff0000u);
;                 *(LAS unsigned*)(img + i * KV_PITCH + kp * 4) = pk2(q0 * __expf(fminf(bi0 - bref0, 80.f)), q1 * __expf(fminf(bi1 - bref1, 80.f)));
;                 *(LAS unsigned*)(img + HG_IMG + i * KV_PITCH + kp * 4) = pk2(kk0[ii] * __expf(fminf(bref0 - bi0, 80.f)), kk1[ii] * __expf(fminf(bref1 - bi1, 80.f)));
;                 *(LAS unsigned*)(img + 2 * HG_IMG + i * KV_PITCH + kp * 4) = pk2(q0 * __expf(bi0), q1 * __expf(bi1));
;                 *(LAS unsigned*)(img + 3 * HG_IMG + i * KV_PITCH + kp * 4) = vraw[ii];
;             }
;         }
;         if (MODE == 0) { if (e8 == 0) *(fv2*)(DEC + (seq * 132 + n) * 64 + 2 * kp) = (fv2){__expf(bend0), __expf(bend1)}; }
	ds_read2_b64 v[104:107], v57 offset1:32
	v_readlane_b32 s22, v253, 34
	s_add_i32 s22, s26, s22
	s_mulk_i32 s22, 0x84
	s_add_i32 s22, s27, s22
	s_waitcnt lgkmcnt(0)
	v_add_f32_e32 v53, 0, v104
	v_add_f32_e32 v89, 0, v105
	v_cndmask_b32_e64 v93, 0, v89, s[4:5]
	v_cndmask_b32_e64 v104, 0, v53, s[4:5]
	v_add_f32_e32 v105, v106, v104
	v_add_f32_e32 v108, v107, v93
	v_cndmask_b32_e64 v93, v93, v108, s[6:7]
	v_cndmask_b32_e64 v108, v104, v105, s[6:7]
	v_add_f32_e32 v53, v53, v106
	v_add_f32_e32 v89, v89, v107
	ds_read2_b64 v[104:107], v57 offset0:64 offset1:96
	s_waitcnt lgkmcnt(0)
	v_add_f32_e32 v109, v104, v108
	v_add_f32_e32 v110, v105, v93
	v_cndmask_b32_e64 v93, v93, v110, s[8:9]
	v_cndmask_b32_e64 v108, v108, v109, s[8:9]
	v_add_f32_e32 v53, v53, v104
	v_add_f32_e32 v89, v89, v105
	v_add_f32_e32 v104, v106, v108
	v_add_f32_e32 v105, v107, v93
	v_cndmask_b32_e64 v93, v93, v105, s[10:11]
	v_cndmask_b32_e64 v108, v108, v104, s[10:11]
	v_add_f32_e32 v53, v53, v106
	v_add_f32_e32 v89, v89, v107
	ds_read2_b64 v[104:107], v57 offset0:128 offset1:160
	s_waitcnt lgkmcnt(0)
	v_add_f32_e32 v109, v104, v108
	v_add_f32_e32 v110, v105, v93
	v_cndmask_b32_e64 v93, v93, v110, s[12:13]
	v_cndmask_b32_e64 v108, v108, v109, s[12:13]
	v_add_f32_e32 v53, v53, v104
	v_add_f32_e32 v89, v89, v105
	v_add_f32_e32 v104, v106, v108
	v_add_f32_e32 v105, v107, v93
	v_cndmask_b32_e64 v93, v93, v105, s[14:15]
	v_cndmask_b32_e64 v108, v108, v104, s[14:15]
	v_add_f32_e32 v53, v53, v106
	v_add_f32_e32 v89, v89, v107
	ds_read2_b64 v[104:107], v57 offset0:192 offset1:224
	s_waitcnt lgkmcnt(0)
	v_add_f32_e32 v109, v104, v108
	v_add_f32_e32 v110, v105, v93
	v_cndmask_b32_e64 v93, v93, v110, s[16:17]
	v_cndmask_b32_e64 v108, v108, v109, s[16:17]
	v_add_f32_e32 v53, v53, v104
	v_add_f32_e32 v104, v89, v105
	v_add_f32_e32 v89, v106, v108
	v_add_f32_e32 v105, v107, v93
	v_cndmask_b32_e64 v93, v93, v105, s[18:19]
	v_cndmask_b32_e64 v105, v108, v89, s[18:19]
	v_add_f32_e32 v89, v53, v106
	v_add_f32_e32 v50, v50, v105
	v_add_f32_e32 v53, v104, v107
	v_add_f32_e32 v51, v51, v93
	v_sub_f32_e32 v50, v89, v50
	v_mul_f32_e32 v50, 0x3fb8aa3b, v50
	v_sub_f32_e32 v51, v53, v51
	v_exp_f32_e32 v50, v50
	v_mul_f32_e32 v51, 0x3fb8aa3b, v51
	v_exp_f32_e32 v51, v51
	v_add_f32_e32 v14, v14, v105
	v_add_f32_e32 v15, v15, v93
	v_sub_f32_e32 v14, v89, v14
	v_mul_f32_e32 v14, 0x3fb8aa3b, v14
	v_sub_f32_e32 v15, v53, v15
	v_mul_f32_e32 v50, v91, v50
	v_exp_f32_e32 v14, v14
	v_mul_f32_e32 v15, 0x3fb8aa3b, v15
	v_add_f32_e32 v10, v10, v105
	v_mul_f32_e32 v51, v90, v51
	v_bfe_u32 v90, v50, 16, 1
	v_exp_f32_e32 v15, v15
	v_add_f32_e32 v11, v11, v93
	v_sub_f32_e32 v10, v89, v10
	v_add3_u32 v50, v50, v90, s79
	v_bfe_u32 v90, v51, 16, 1
	v_mul_f32_e32 v10, 0x3fb8aa3b, v10
	v_sub_f32_e32 v11, v53, v11
	v_lshrrev_b32_e32 v50, 16, v50
	v_add3_u32 v51, v51, v90, s79
	v_exp_f32_e32 v10, v10
	v_mul_f32_e32 v11, 0x3fb8aa3b, v11
	v_add_f32_e32 v8, v8, v105
	v_and_or_b32 v50, v51, s82, v50
	v_mul_f32_e32 v14, v95, v14
	v_exp_f32_e32 v11, v11
	v_add_f32_e32 v9, v9, v93
	v_sub_f32_e32 v8, v89, v8
	ds_write2st64_b32 v61, v50, v88 offset1:36
	v_mul_f32_e32 v15, v94, v15
	v_bfe_u32 v50, v14, 16, 1
	v_mul_f32_e32 v8, 0x3fb8aa3b, v8
	v_sub_f32_e32 v9, v53, v9
	v_add3_u32 v14, v14, v50, s79
	v_bfe_u32 v50, v15, 16, 1
	v_exp_f32_e32 v8, v8
	v_mul_f32_e32 v9, 0x3fb8aa3b, v9
	v_add_f32_e32 v6, v6, v105
	v_lshrrev_b32_e32 v14, 16, v14
	v_add3_u32 v15, v15, v50, s79
	v_mul_f32_e32 v10, v97, v10
	v_exp_f32_e32 v9, v9
	v_add_f32_e32 v7, v7, v93
	v_sub_f32_e32 v6, v89, v6
	v_and_or_b32 v14, v15, s82, v14
	v_mul_f32_e32 v11, v96, v11
	v_bfe_u32 v15, v10, 16, 1
	v_mul_f32_e32 v6, 0x3fb8aa3b, v6
	v_sub_f32_e32 v7, v53, v7
	v_add3_u32 v10, v10, v15, s79
	v_bfe_u32 v15, v11, 16, 1
	v_exp_f32_e32 v6, v6
	v_mul_f32_e32 v7, 0x3fb8aa3b, v7
	v_lshrrev_b32_e32 v10, 16, v10
	v_add3_u32 v11, v11, v15, s79
	v_mul_f32_e32 v8, v99, v8
	v_exp_f32_e32 v7, v7
	v_add_f32_e32 v4, v4, v105
	v_and_or_b32 v10, v11, s82, v10
	v_mul_f32_e32 v9, v98, v9
	v_bfe_u32 v11, v8, 16, 1
	v_add_f32_e32 v5, v5, v93
	v_sub_f32_e32 v4, v89, v4
	v_add3_u32 v8, v8, v11, s79
	v_bfe_u32 v11, v9, 16, 1
	v_mul_f32_e32 v4, 0x3fb8aa3b, v4
	v_sub_f32_e32 v5, v53, v5
	v_lshrrev_b32_e32 v8, 16, v8
	v_add3_u32 v9, v9, v11, s79
	v_mul_f32_e32 v6, v101, v6
	v_exp_f32_e32 v4, v4
	v_mul_f32_e32 v5, 0x3fb8aa3b, v5
	v_add_f32_e32 v2, v2, v105
	v_and_or_b32 v8, v9, s82, v8
	v_mul_f32_e32 v7, v100, v7
	v_bfe_u32 v9, v6, 16, 1
	v_exp_f32_e32 v5, v5
	v_add_f32_e32 v3, v3, v93
	v_sub_f32_e32 v2, v89, v2
	v_add3_u32 v6, v6, v9, s79
	v_bfe_u32 v9, v7, 16, 1
	v_mul_f32_e32 v2, 0x3fb8aa3b, v2
	v_sub_f32_e32 v3, v53, v3
	v_lshrrev_b32_e32 v6, 16, v6
	v_add3_u32 v7, v7, v9, s79
	v_exp_f32_e32 v2, v2
	v_mul_f32_e32 v3, 0x3fb8aa3b, v3
	ds_write2_b32 v62, v14, v10 offset1:36
	v_add_u32_e32 v10, 0x2400, v62
	v_and_or_b32 v6, v7, s82, v6
	v_mul_f32_e32 v4, v103, v4
	v_exp_f32_e32 v3, v3
	v_add_f32_e32 v0, v0, v105
	ds_write2_b32 v10, v86, v87 offset1:36
	ds_write2_b32 v62, v8, v6 offset0:72 offset1:108
	ds_write2_b32 v10, v84, v85 offset0:72 offset1:108
	v_mul_f32_e32 v5, v102, v5
	v_bfe_u32 v6, v4, 16, 1
	v_add_f32_e32 v1, v1, v93
	v_sub_f32_e32 v0, v89, v0
	v_add3_u32 v4, v4, v6, s79
	v_bfe_u32 v6, v5, 16, 1
	v_mul_f32_e32 v0, 0x3fb8aa3b, v0
	v_sub_f32_e32 v1, v53, v1
	v_lshrrev_b32_e32 v4, 16, v4
	v_add3_u32 v5, v5, v6, s79
	v_mul_f32_e32 v2, v13, v2
	v_exp_f32_e32 v0, v0
	v_mul_f32_e32 v1, 0x3fb8aa3b, v1
	v_and_or_b32 v4, v5, s82, v4
	v_mul_f32_e32 v3, v12, v3
	v_bfe_u32 v5, v2, 16, 1
	v_exp_f32_e32 v1, v1
	v_add3_u32 v2, v2, v5, s79
	v_bfe_u32 v5, v3, 16, 1
	v_lshrrev_b32_e32 v2, 16, v2
	v_add3_u32 v3, v3, v5, s79
	v_and_or_b32 v2, v3, s82, v2
	v_mul_f32_e32 v0, v92, v0
	ds_write2_b32 v62, v4, v2 offset0:144 offset1:180
	ds_write2_b32 v10, v82, v83 offset0:144 offset1:180
	v_mul_f32_e32 v1, v52, v1
	v_bfe_u32 v2, v0, 16, 1
	v_add3_u32 v0, v0, v2, s79
	v_bfe_u32 v2, v1, 16, 1
	v_lshrrev_b32_e32 v0, 16, v0
	v_add3_u32 v1, v1, v2, s79
	v_and_or_b32 v0, v1, s82, v0
	ds_write_b32 v62, v0 offset:864
	ds_write_b32 v62, v80 offset:10080
	s_and_saveexec_b64 s[26:27], s[20:21]
	s_cbranch_execz .LBB0_241
	v_mul_f32_e32 v0, 0x3fb8aa3b, v89
	v_mul_f32_e32 v1, 0x3fb8aa3b, v53
	v_exp_f32_e32 v0, v0
	v_exp_f32_e32 v1, v1
	s_lshl_b32 s34, s22, 6
	s_ashr_i32 s35, s34, 31
	v_lshl_add_u64 v[2:3], s[34:35], 2, v[16:17]
	global_store_dwordx2 v[2:3], v[0:1], off
	s_branch .LBB0_241

.LBB0_393:
	s_and_b32 s54, s62, 3
	s_cmp_gt_i32 s59, 3
	s_cselect_b32 s62, 0x87, 3
	s_add_i32 s62, s62, s55
	s_add_i32 s64, s61, 63
	s_add_i32 s55, s2, s62
	s_lshl_b32 s62, s54, 6
	v_sub_u32_e32 v9, s64, v49
	v_add_u32_e32 v13, s61, v49
	v_or_b32_e32 v3, s62, v51
	v_or_b32_e32 v5, s62, v52
	v_or_b32_e32 v7, s62, v48
	v_cndmask_b32_e64 v9, v9, v13, s[0:1]
	v_mov_b64_e32 v[14:15], s[84:85]
	v_mad_i64_i32 v[16:17], s[62:63], v9, s77, v[14:15]
	v_lshlrev_b32_e32 v18, 1, v5
	v_mov_b32_e32 v19, v161
	v_lshlrev_b32_e32 v98, 1, v7
	v_mov_b32_e32 v99, v161
	v_lshlrev_b32_e32 v100, 1, v3
	v_mov_b32_e32 v101, v161
	v_sub_u32_e32 v3, s64, v58
	v_add_u32_e32 v5, s61, v58
	v_lshl_add_u64 v[74:75], v[16:17], 0, v[18:19]
	v_lshl_add_u64 v[76:77], v[16:17], 0, v[98:99]
	v_lshl_add_u64 v[16:17], v[16:17], 0, v[100:101]
	v_cndmask_b32_e64 v3, v3, v5, s[0:1]
	global_load_dword v74, v[74:75], off nt
	v_add_u32_e32 v5, s61, v57
	global_load_dword v79, v[16:17], off nt
	v_mad_i64_i32 v[16:17], s[62:63], v3, s77, v[14:15]
	v_lshl_add_u64 v[80:81], v[16:17], 0, v[18:19]
	v_sub_u32_e32 v3, s64, v57
	global_load_dword v76, v[76:77], off offset:3584 nt
	v_cndmask_b32_e64 v3, v3, v5, s[0:1]
	global_load_dword v75, v[80:81], off nt
	v_lshl_add_u64 v[80:81], v[16:17], 0, v[98:99]
	v_lshl_add_u64 v[16:17], v[16:17], 0, v[100:101]
	global_load_dword v78, v[80:81], off offset:3584 nt
	v_add_u32_e32 v5, s61, v56
	global_load_dword v80, v[16:17], off nt
	v_mad_i64_i32 v[16:17], s[62:63], v3, s77, v[14:15]
	v_lshl_add_u64 v[82:83], v[16:17], 0, v[18:19]
	v_sub_u32_e32 v3, s64, v56
	global_load_dword v77, v[82:83], off nt
	v_lshl_add_u64 v[82:83], v[16:17], 0, v[98:99]
	v_lshl_add_u64 v[16:17], v[16:17], 0, v[100:101]
	v_cndmask_b32_e64 v3, v3, v5, s[0:1]
	global_load_dword v82, v[82:83], off offset:3584 nt
	v_add_u32_e32 v5, s61, v55
	global_load_dword v85, v[16:17], off nt
	v_mad_i64_i32 v[16:17], s[62:63], v3, s77, v[14:15]
	v_lshl_add_u64 v[86:87], v[16:17], 0, v[18:19]
	v_sub_u32_e32 v3, s64, v55
	global_load_dword v81, v[86:87], off nt
	v_lshl_add_u64 v[86:87], v[16:17], 0, v[98:99]
	v_lshl_add_u64 v[16:17], v[16:17], 0, v[100:101]
	v_cndmask_b32_e64 v3, v3, v5, s[0:1]
	global_load_dword v84, v[86:87], off offset:3584 nt
	v_add_u32_e32 v5, s61, v54
	global_load_dword v87, v[16:17], off nt
	v_mad_i64_i32 v[16:17], s[62:63], v3, s77, v[14:15]
	v_lshl_add_u64 v[88:89], v[16:17], 0, v[18:19]
	v_sub_u32_e32 v3, s64, v54
	v_readlane_b32 s36, v254, 4
	global_load_dword v83, v[88:89], off nt
	v_lshl_add_u64 v[88:89], v[16:17], 0, v[98:99]
	v_lshl_add_u64 v[16:17], v[16:17], 0, v[100:101]
	v_cndmask_b32_e64 v3, v3, v5, s[0:1]
	s_add_i32 s60, s60, s36
	global_load_dword v86, v[88:89], off offset:3584 nt
	s_lshl_b32 s60, s60, 2
	global_load_dword v89, v[16:17], off nt
	v_mad_i64_i32 v[16:17], s[62:63], v3, s77, v[14:15]
	v_lshl_add_u64 v[90:91], v[16:17], 0, v[18:19]
	v_sub_u32_e32 v3, s64, v53
	v_add_u32_e32 v5, s61, v53
	global_load_dword v88, v[90:91], off nt
	v_lshl_add_u64 v[90:91], v[16:17], 0, v[98:99]
	v_lshl_add_u64 v[16:17], v[16:17], 0, v[100:101]
	v_cndmask_b32_e64 v3, v3, v5, s[0:1]
	s_and_b64 s[62:63], s[0:1], exec
	global_load_dword v91, v[90:91], off offset:3584 nt
	v_add_u32_e32 v5, s61, v50
	global_load_dword v94, v[16:17], off nt
	v_mad_i64_i32 v[16:17], s[62:63], v3, s77, v[14:15]
	v_sub_u32_e32 v3, s64, v50
	s_cselect_b32 s55, s59, s55
	s_or_b32 s54, s60, s54
	v_lshl_add_u64 v[92:93], v[16:17], 0, v[18:19]
	v_cndmask_b32_e64 v3, v3, v5, s[0:1]
	s_mulk_i32 s54, 0x84
	global_load_dword v90, v[92:93], off nt
	v_lshl_add_u64 v[92:93], v[16:17], 0, v[98:99]
	v_lshl_add_u64 v[16:17], v[16:17], 0, v[100:101]
	v_mad_i64_i32 v[14:15], s[62:63], v3, s77, v[14:15]
	s_add_i32 s54, s55, s54
	global_load_dword v93, v[92:93], off offset:3584 nt
	s_ashr_i32 s55, s54, 31
	global_load_dword v96, v[16:17], off nt
	v_lshl_add_u64 v[16:17], v[14:15], 0, v[18:19]
	global_load_dword v92, v[16:17], off nt
	v_lshl_add_u64 v[16:17], v[14:15], 0, v[98:99]
	v_lshl_add_u64 v[14:15], v[14:15], 0, v[100:101]
	s_lshl_b64 s[54:55], s[54:55], 13
	global_load_dword v95, v[16:17], off offset:3584 nt
	global_load_dword v97, v[14:15], off nt
	v_lshl_add_u64 v[14:15], v[46:47], 0, s[54:55]
	global_load_dword v105, v[14:15], off nt
	global_load_dword v104, v[14:15], off offset:128 nt
	global_load_dword v103, v[14:15], off offset:256 nt
	global_load_dword v102, v[14:15], off offset:384 nt
	global_load_dword v101, v[14:15], off offset:512 nt
	global_load_dword v100, v[14:15], off offset:640 nt
	global_load_dword v99, v[14:15], off offset:768 nt
	global_load_dword v98, v[14:15], off offset:896 nt
	v_readlane_b32 s62, v255, 21
	v_readlane_b32 s63, v255, 22
	s_branch .LBB0_394

; DI float sigmoid_f(float x) { return 1.f / (1.f + __expf(-x)); }
; template <int MODE> DI void hgrn_chunk_phase(const Args& A, int wave_s, int l, bool need_ctx, LAS unsigned char* lds) {
;     ...
;         const float lb0 = C.SM[SM_LOWER + (l * 2 + dir) * 256 + hd * 64 + 2 * kp], lb1 = C.SM[SM_LOWER + (l * 2 + dir) * 256 + hd * 64 + 2 * kp + 1];
;         float cum0[8], cum1[8], kk0[8], kk1[8]; float bl0 = 0.f, bl1 = 0.f;
;         unsigned vraw[8], qraw[8], spv[8];
; #pragma unroll
;         for (int ii = 0; ii < 8; ++ii) {
;             const float pf0 = __builtin_bit_cast(float, npf[ii] << 16), pf1 = __builtin_bit_cast(float, npf[ii] & 0xffff0000u);
;             const float f0 = fmaxf(lb0 + (1.f - lb0) * sigmoid_f(pf0), 1e-30f), f1 = fmaxf(lb1 + (1.f - lb1) * sigmoid_f(pf1), 1e-30f);
;             bl0 += __logf(f0); bl1 += __logf(f1); cum0[ii] = bl0; cum1[ii] = bl1; kk0[ii] = 1.f - f0; kk1[ii] = 1.f - f1;
;             vraw[ii] = nv[ii]; qraw[ii] = nq[ii]; spv[ii] = nsp[ii]; }
;         bf16* SL = (bf16*)C.ST + ((size_t)(seq * 132 + n)) * 4096;
;         if (u + (int)gridDim.x < nunits) HG_FETCH(u + (int)gridDim.x);
;         __syncthreads();
.LBB0_394:
	v_lshlrev_b32_e32 v3, 16, v2
	v_mul_f32_e32 v3, 0xbfb8aa3b, v3
	v_exp_f32_e32 v3, v3
	v_and_b32_e32 v2, 0xffff0000, v2
	v_mul_f32_e32 v2, 0xbfb8aa3b, v2
	v_exp_f32_e32 v2, v2
	v_add_f32_e32 v3, 1.0, v3
	v_div_scale_f32 v5, s[54:55], v3, v3, 1.0
	v_rcp_f32_e32 v7, v5
	s_waitcnt vmcnt(32)
	v_sub_f32_e32 v112, 1.0, v0
	v_add_f32_e32 v2, 1.0, v2
	v_sub_f32_e32 v111, 1.0, v1
	v_fma_f32 v9, -v5, v7, 1.0
	v_fmac_f32_e32 v7, v9, v7
	v_div_scale_f32 v9, vcc, 1.0, v3, 1.0
	v_mul_f32_e32 v13, v9, v7
	v_fma_f32 v14, -v5, v13, v9
	v_fmac_f32_e32 v13, v14, v7
	v_fma_f32 v5, -v5, v13, v9
	v_div_fmas_f32 v5, v5, v7, v13
	v_div_fixup_f32 v3, v5, v3, 1.0
	v_fma_f32 v3, v3, v112, v0
	v_max_f32_e32 v5, 0xda24260, v3
	v_div_scale_f32 v3, s[54:55], v2, v2, 1.0
	v_rcp_f32_e32 v7, v3
	v_sub_f32_e32 v108, 1.0, v5
	s_barrier
	v_fma_f32 v9, -v3, v7, 1.0
	v_fmac_f32_e32 v7, v9, v7
	v_div_scale_f32 v9, vcc, 1.0, v2, 1.0
	v_mul_f32_e32 v13, v9, v7
	v_fma_f32 v14, -v3, v13, v9
	v_fmac_f32_e32 v13, v14, v7
	v_fma_f32 v3, -v3, v13, v9
	v_div_fmas_f32 v3, v3, v7, v13
	v_div_fixup_f32 v2, v3, v2, 1.0
	v_fma_f32 v2, v2, v111, v1
	v_cmp_gt_f32_e32 vcc, s78, v5
	v_max_f32_e32 v7, 0xda24260, v2
	v_sub_f32_e32 v107, 1.0, v7
	v_cndmask_b32_e64 v2, 0, 32, vcc
	v_ldexp_f32 v2, v5, v2
	v_log_f32_e32 v2, v2
	v_lshlrev_b32_e32 v5, 16, v4
	v_mul_f32_e32 v5, 0xbfb8aa3b, v5
	v_exp_f32_e32 v5, v5
	v_mul_f32_e32 v3, 0x3f317217, v2
	v_fma_f32 v3, v2, s91, -v3
	v_fmac_f32_e32 v3, 0x3377d1cf, v2
	v_fmac_f32_e32 v3, 0x3f317217, v2
	v_cmp_lt_f32_e64 s[54:55], |v2|, s80
	v_add_f32_e32 v5, 1.0, v5
	v_and_b32_e32 v4, 0xffff0000, v4
	v_cndmask_b32_e64 v2, v2, v3, s[54:55]
	v_cndmask_b32_e32 v3, 0, v249, vcc
	v_cmp_gt_f32_e32 vcc, s78, v7
	v_sub_f32_e32 v2, v2, v3
	v_mul_f32_e32 v4, 0xbfb8aa3b, v4
	v_cndmask_b32_e64 v3, 0, 32, vcc
	v_ldexp_f32 v3, v7, v3
	v_log_f32_e32 v3, v3
	v_exp_f32_e32 v4, v4
	v_readlane_b32 s36, v254, 6
	v_mul_f32_e32 v9, 0x3f317217, v3
	v_fma_f32 v9, v3, s91, -v9
	v_fmac_f32_e32 v9, 0x3377d1cf, v3
	v_fmac_f32_e32 v9, 0x3f317217, v3
	v_cmp_lt_f32_e64 s[54:55], |v3|, s80
	v_add_f32_e32 v4, 1.0, v4
	v_readlane_b32 s37, v254, 7
	v_cndmask_b32_e64 v3, v3, v9, s[54:55]
	v_cndmask_b32_e32 v9, 0, v249, vcc
	v_div_scale_f32 v7, s[54:55], v5, v5, 1.0
	v_sub_f32_e32 v3, v3, v9
	v_rcp_f32_e32 v9, v7
	s_nop 0
	v_fma_f32 v13, -v7, v9, 1.0
	v_fmac_f32_e32 v9, v13, v9
	v_div_scale_f32 v13, vcc, 1.0, v5, 1.0
	v_mul_f32_e32 v14, v13, v9
	v_fma_f32 v15, -v7, v14, v13
	v_fmac_f32_e32 v14, v15, v9
	v_fma_f32 v7, -v7, v14, v13
	v_div_fmas_f32 v7, v7, v9, v14
	v_div_fixup_f32 v5, v7, v5, 1.0
	v_fma_f32 v5, v5, v112, v0
	v_max_f32_e32 v7, 0xda24260, v5
	v_div_scale_f32 v5, s[54:55], v4, v4, 1.0
	v_rcp_f32_e32 v9, v5
	v_sub_f32_e32 v110, 1.0, v7
	v_fma_f32 v13, -v5, v9, 1.0
	v_fmac_f32_e32 v9, v13, v9
	v_div_scale_f32 v13, vcc, 1.0, v4, 1.0
	v_mul_f32_e32 v14, v13, v9
	v_fma_f32 v15, -v5, v14, v13
	v_fmac_f32_e32 v14, v15, v9
	v_fma_f32 v5, -v5, v14, v13
	v_div_fmas_f32 v5, v5, v9, v14
	v_div_fixup_f32 v4, v5, v4, 1.0
	v_fma_f32 v4, v4, v111, v1
	v_cmp_gt_f32_e32 vcc, s78, v7
	v_max_f32_e32 v9, 0xda24260, v4
	v_sub_f32_e32 v109, 1.0, v9
	v_cndmask_b32_e64 v4, 0, 32, vcc
	v_ldexp_f32 v4, v7, v4
	v_log_f32_e32 v4, v4
	v_lshlrev_b32_e32 v7, 16, v6
	v_mul_f32_e32 v7, 0xbfb8aa3b, v7
	v_exp_f32_e32 v7, v7
	v_mul_f32_e32 v5, 0x3f317217, v4
	v_fma_f32 v5, v4, s91, -v5
	v_fmac_f32_e32 v5, 0x3377d1cf, v4
	v_fmac_f32_e32 v5, 0x3f317217, v4
	v_cmp_lt_f32_e64 s[54:55], |v4|, s80
	v_add_f32_e32 v7, 1.0, v7
	v_and_b32_e32 v6, 0xffff0000, v6
	v_cndmask_b32_e64 v4, v4, v5, s[54:55]
	v_cndmask_b32_e32 v5, 0, v249, vcc
	v_cmp_gt_f32_e32 vcc, s78, v9
	v_sub_f32_e32 v4, v4, v5
	v_mul_f32_e32 v6, 0xbfb8aa3b, v6
	v_cndmask_b32_e64 v5, 0, 32, vcc
	v_ldexp_f32 v5, v9, v5
	v_log_f32_e32 v5, v5
	v_exp_f32_e32 v6, v6
	v_mul_f32_e32 v13, 0x3f317217, v5
	v_fma_f32 v13, v5, s91, -v13
	v_fmac_f32_e32 v13, 0x3377d1cf, v5
	v_fmac_f32_e32 v13, 0x3f317217, v5
	v_cmp_lt_f32_e64 s[54:55], |v5|, s80
	v_add_f32_e32 v6, 1.0, v6
	s_nop 0
	v_cndmask_b32_e64 v5, v5, v13, s[54:55]
	v_cndmask_b32_e32 v13, 0, v249, vcc
	v_div_scale_f32 v9, s[54:55], v7, v7, 1.0
	v_sub_f32_e32 v5, v5, v13
	v_rcp_f32_e32 v13, v9
	s_nop 0
	v_fma_f32 v14, -v9, v13, 1.0
	v_fmac_f32_e32 v13, v14, v13
	v_div_scale_f32 v14, vcc, 1.0, v7, 1.0
	v_mul_f32_e32 v15, v14, v13
	v_fma_f32 v16, -v9, v15, v14
	v_fmac_f32_e32 v15, v16, v13
	v_fma_f32 v9, -v9, v15, v14
	v_div_fmas_f32 v9, v9, v13, v15
	v_div_fixup_f32 v7, v9, v7, 1.0
	v_fma_f32 v7, v7, v112, v0
	v_max_f32_e32 v9, 0xda24260, v7
	v_div_scale_f32 v7, s[54:55], v6, v6, 1.0
	v_rcp_f32_e32 v13, v7
	v_sub_f32_e32 v114, 1.0, v9
	v_fma_f32 v14, -v7, v13, 1.0
	v_fmac_f32_e32 v13, v14, v13
	v_div_scale_f32 v14, vcc, 1.0, v6, 1.0
	v_mul_f32_e32 v15, v14, v13
	v_fma_f32 v16, -v7, v15, v14
	v_fmac_f32_e32 v15, v16, v13
	v_fma_f32 v7, -v7, v15, v14
	v_div_fmas_f32 v7, v7, v13, v15
	v_div_fixup_f32 v6, v7, v6, 1.0
	v_fma_f32 v6, v6, v111, v1
	v_cmp_gt_f32_e32 vcc, s78, v9
	v_max_f32_e32 v13, 0xda24260, v6
	v_sub_f32_e32 v113, 1.0, v13
	v_cndmask_b32_e64 v6, 0, 32, vcc
	v_ldexp_f32 v6, v9, v6
	v_log_f32_e32 v6, v6
	v_lshlrev_b32_e32 v9, 16, v8
	v_mul_f32_e32 v9, 0xbfb8aa3b, v9
	v_exp_f32_e32 v9, v9
	v_mul_f32_e32 v7, 0x3f317217, v6
	v_fma_f32 v7, v6, s91, -v7
	v_fmac_f32_e32 v7, 0x3377d1cf, v6
	v_fmac_f32_e32 v7, 0x3f317217, v6
	v_cmp_lt_f32_e64 s[54:55], |v6|, s80
	v_add_f32_e32 v9, 1.0, v9
	v_and_b32_e32 v8, 0xffff0000, v8
	v_cndmask_b32_e64 v6, v6, v7, s[54:55]
	v_cndmask_b32_e32 v7, 0, v249, vcc
	v_cmp_gt_f32_e32 vcc, s78, v13
	v_sub_f32_e32 v6, v6, v7
	v_mul_f32_e32 v8, 0xbfb8aa3b, v8
	v_cndmask_b32_e64 v7, 0, 32, vcc
; DI float sigmoid_f(float x) { return 1.f / (1.f + __expf(-x)); }
; template <int MODE> DI void hgrn_chunk_phase(const Args& A, int wave_s, int l, bool need_ctx, LAS unsigned char* lds) {
;     ...
;         for (int ii = 0; ii < 8; ++ii) {
;             const float pf0 = __builtin_bit_cast(float, npf[ii] << 16), pf1 = __builtin_bit_cast(float, npf[ii] & 0xffff0000u);
;             const float f0 = fmaxf(lb0 + (1.f - lb0) * sigmoid_f(pf0), 1e-30f), f1 = fmaxf(lb1 + (1.f - lb1) * sigmoid_f(pf1), 1e-30f);
;             bl0 += __logf(f0); bl1 += __logf(f1); cum0[ii] = bl0; cum1[ii] = bl1; kk0[ii] = 1.f - f0; kk1[ii] = 1.f - f1;
;             vraw[ii] = nv[ii]; qraw[ii] = nq[ii]; spv[ii] = nsp[ii]; }
	v_ldexp_f32 v7, v13, v7
	v_log_f32_e32 v7, v7
	v_exp_f32_e32 v8, v8
	v_mul_f32_e32 v14, 0x3f317217, v7
	v_fma_f32 v14, v7, s91, -v14
	v_fmac_f32_e32 v14, 0x3377d1cf, v7
	v_fmac_f32_e32 v14, 0x3f317217, v7
	v_cmp_lt_f32_e64 s[54:55], |v7|, s80
	v_add_f32_e32 v8, 1.0, v8
	s_nop 0
	v_cndmask_b32_e64 v7, v7, v14, s[54:55]
	v_cndmask_b32_e32 v14, 0, v249, vcc
	v_div_scale_f32 v13, s[54:55], v9, v9, 1.0
	v_sub_f32_e32 v7, v7, v14
	v_rcp_f32_e32 v14, v13
	s_nop 0
	v_fma_f32 v15, -v13, v14, 1.0
	v_fmac_f32_e32 v14, v15, v14
	v_div_scale_f32 v15, vcc, 1.0, v9, 1.0
	v_mul_f32_e32 v16, v15, v14
	v_fma_f32 v17, -v13, v16, v15
	v_fmac_f32_e32 v16, v17, v14
	v_fma_f32 v13, -v13, v16, v15
	v_div_fmas_f32 v13, v13, v14, v16
	v_div_fixup_f32 v9, v13, v9, 1.0
	v_fma_f32 v9, v9, v112, v0
	v_max_f32_e32 v13, 0xda24260, v9
	v_div_scale_f32 v9, s[54:55], v8, v8, 1.0
	v_rcp_f32_e32 v14, v9
	v_sub_f32_e32 v116, 1.0, v13
	v_fma_f32 v15, -v9, v14, 1.0
	v_fmac_f32_e32 v14, v15, v14
	v_div_scale_f32 v15, vcc, 1.0, v8, 1.0
	v_mul_f32_e32 v16, v15, v14
	v_fma_f32 v17, -v9, v16, v15
	v_fmac_f32_e32 v16, v17, v14
	v_fma_f32 v9, -v9, v16, v15
	v_div_fmas_f32 v9, v9, v14, v16
	v_div_fixup_f32 v8, v9, v8, 1.0
	v_fma_f32 v8, v8, v111, v1
	v_cmp_gt_f32_e32 vcc, s78, v13
	v_max_f32_e32 v14, 0xda24260, v8
	v_sub_f32_e32 v115, 1.0, v14
	v_cndmask_b32_e64 v8, 0, 32, vcc
	v_ldexp_f32 v8, v13, v8
	v_log_f32_e32 v8, v8
	v_lshlrev_b32_e32 v13, 16, v12
	v_mul_f32_e32 v13, 0xbfb8aa3b, v13
	v_exp_f32_e32 v13, v13
	v_mul_f32_e32 v9, 0x3f317217, v8
	v_fma_f32 v9, v8, s91, -v9
	v_fmac_f32_e32 v9, 0x3377d1cf, v8
	v_fmac_f32_e32 v9, 0x3f317217, v8
	v_cmp_lt_f32_e64 s[54:55], |v8|, s80
	v_add_f32_e32 v13, 1.0, v13
	v_and_b32_e32 v12, 0xffff0000, v12
	v_cndmask_b32_e64 v8, v8, v9, s[54:55]
	v_cndmask_b32_e32 v9, 0, v249, vcc
	v_cmp_gt_f32_e32 vcc, s78, v14
	v_sub_f32_e32 v8, v8, v9
	v_mul_f32_e32 v12, 0xbfb8aa3b, v12
	v_cndmask_b32_e64 v9, 0, 32, vcc
	v_ldexp_f32 v9, v14, v9
	v_log_f32_e32 v9, v9
	v_exp_f32_e32 v12, v12
	v_mul_f32_e32 v15, 0x3f317217, v9
	v_fma_f32 v15, v9, s91, -v15
	v_fmac_f32_e32 v15, 0x3377d1cf, v9
	v_fmac_f32_e32 v15, 0x3f317217, v9
	v_cmp_lt_f32_e64 s[54:55], |v9|, s80
	v_add_f32_e32 v12, 1.0, v12
	s_nop 0
	v_cndmask_b32_e64 v9, v9, v15, s[54:55]
	v_cndmask_b32_e32 v15, 0, v249, vcc
	v_div_scale_f32 v14, s[54:55], v13, v13, 1.0
	v_sub_f32_e32 v9, v9, v15
	v_rcp_f32_e32 v15, v14
	s_nop 0
	v_fma_f32 v16, -v14, v15, 1.0
	v_fmac_f32_e32 v15, v16, v15
	v_div_scale_f32 v16, vcc, 1.0, v13, 1.0
	v_mul_f32_e32 v17, v16, v15
	v_fma_f32 v18, -v14, v17, v16
	v_fmac_f32_e32 v17, v18, v15
	v_fma_f32 v14, -v14, v17, v16
	v_div_fmas_f32 v14, v14, v15, v17
	v_div_fixup_f32 v13, v14, v13, 1.0
	v_div_scale_f32 v14, s[54:55], v12, v12, 1.0
	v_rcp_f32_e32 v15, v14
	v_fma_f32 v13, v13, v112, v0
	v_max_f32_e32 v13, 0xda24260, v13
	v_sub_f32_e32 v118, 1.0, v13
	v_fma_f32 v16, -v14, v15, 1.0
	v_fmac_f32_e32 v15, v16, v15
	v_div_scale_f32 v16, vcc, 1.0, v12, 1.0
	v_mul_f32_e32 v17, v16, v15
	v_fma_f32 v18, -v14, v17, v16
	v_fmac_f32_e32 v17, v18, v15
	v_fma_f32 v14, -v14, v17, v16
	v_div_fmas_f32 v14, v14, v15, v17
	v_cmp_gt_f32_e32 vcc, s78, v13
	v_div_fixup_f32 v12, v14, v12, 1.0
	v_fma_f32 v12, v12, v111, v1
	v_cndmask_b32_e64 v14, 0, 32, vcc
	v_ldexp_f32 v14, v13, v14
	v_log_f32_e32 v14, v14
	v_max_f32_e32 v12, 0xda24260, v12
	v_sub_f32_e32 v117, 1.0, v12
	v_mul_f32_e32 v15, 0x3f317217, v14
	v_fma_f32 v15, v14, s91, -v15
	v_fmac_f32_e32 v15, 0x3377d1cf, v14
	v_fmac_f32_e32 v15, 0x3f317217, v14
	v_cmp_lt_f32_e64 s[54:55], |v14|, s80
	s_nop 1
	v_cndmask_b32_e64 v14, v14, v15, s[54:55]
	v_cndmask_b32_e32 v15, 0, v249, vcc
	v_cmp_gt_f32_e32 vcc, s78, v12
	v_sub_f32_e32 v14, v14, v15
	s_nop 0
	v_cndmask_b32_e64 v15, 0, 32, vcc
	v_ldexp_f32 v15, v12, v15
	v_log_f32_e32 v15, v15
	v_lshlrev_b32_e32 v12, 16, v11
	v_mul_f32_e32 v12, 0xbfb8aa3b, v12
	v_exp_f32_e32 v12, v12
	v_mul_f32_e32 v16, 0x3f317217, v15
	v_fma_f32 v16, v15, s91, -v16
	v_fmac_f32_e32 v16, 0x3377d1cf, v15
	v_fmac_f32_e32 v16, 0x3f317217, v15
	v_cmp_lt_f32_e64 s[54:55], |v15|, s80
	v_add_f32_e32 v12, 1.0, v12
	v_and_b32_e32 v11, 0xffff0000, v11
	v_cndmask_b32_e64 v15, v15, v16, s[54:55]
	v_cndmask_b32_e32 v16, 0, v249, vcc
	v_div_scale_f32 v13, s[54:55], v12, v12, 1.0
	v_sub_f32_e32 v15, v15, v16
	v_rcp_f32_e32 v16, v13
	v_mul_f32_e32 v11, 0xbfb8aa3b, v11
	v_exp_f32_e32 v11, v11
	v_fma_f32 v17, -v13, v16, 1.0
	v_fmac_f32_e32 v16, v17, v16
	v_div_scale_f32 v17, vcc, 1.0, v12, 1.0
	v_mul_f32_e32 v18, v17, v16
	v_fma_f32 v19, -v13, v18, v17
	v_fmac_f32_e32 v18, v19, v16
	v_fma_f32 v13, -v13, v18, v17
	v_div_fmas_f32 v13, v13, v16, v18
	v_add_f32_e32 v11, 1.0, v11
	v_div_fixup_f32 v12, v13, v12, 1.0
	v_div_scale_f32 v13, s[54:55], v11, v11, 1.0
	v_rcp_f32_e32 v16, v13
	v_fma_f32 v12, v12, v112, v0
	v_max_f32_e32 v12, 0xda24260, v12
	v_sub_f32_e32 v120, 1.0, v12
	v_fma_f32 v17, -v13, v16, 1.0
	v_fmac_f32_e32 v16, v17, v16
	v_div_scale_f32 v17, vcc, 1.0, v11, 1.0
	v_mul_f32_e32 v18, v17, v16
	v_fma_f32 v19, -v13, v18, v17
	v_fmac_f32_e32 v18, v19, v16
	v_fma_f32 v13, -v13, v18, v17
	v_div_fmas_f32 v13, v13, v16, v18
	v_cmp_gt_f32_e32 vcc, s78, v12
	v_div_fixup_f32 v11, v13, v11, 1.0
	v_fma_f32 v11, v11, v111, v1
	v_cndmask_b32_e64 v13, 0, 32, vcc
	v_ldexp_f32 v13, v12, v13
	v_log_f32_e32 v13, v13
	v_max_f32_e32 v11, 0xda24260, v11
	v_sub_f32_e32 v119, 1.0, v11
	v_mul_f32_e32 v16, 0x3f317217, v13
	v_fma_f32 v16, v13, s91, -v16
	v_fmac_f32_e32 v16, 0x3377d1cf, v13
	v_fmac_f32_e32 v16, 0x3f317217, v13
	v_cmp_lt_f32_e64 s[54:55], |v13|, s80
	s_nop 1
	v_cndmask_b32_e64 v13, v13, v16, s[54:55]
	v_cndmask_b32_e32 v16, 0, v249, vcc
; #define LAS __attribute__((address_space(3)))
; DI float sigmoid_f(float x) { return 1.f / (1.f + __expf(-x)); }
; template <int MODE> DI void hgrn_chunk_phase(const Args& A, int wave_s, int l, bool need_ctx, LAS unsigned char* lds) {
;     ...
;         for (int ii = 0; ii < 8; ++ii) {
;             const float pf0 = __builtin_bit_cast(float, npf[ii] << 16), pf1 = __builtin_bit_cast(float, npf[ii] & 0xffff0000u);
;             const float f0 = fmaxf(lb0 + (1.f - lb0) * sigmoid_f(pf0), 1e-30f), f1 = fmaxf(lb1 + (1.f - lb1) * sigmoid_f(pf1), 1e-30f);
;             bl0 += __logf(f0); bl1 += __logf(f1); cum0[ii] = bl0; cum1[ii] = bl1; kk0[ii] = 1.f - f0; kk1[ii] = 1.f - f1;
;             vraw[ii] = nv[ii]; qraw[ii] = nq[ii]; spv[ii] = nsp[ii]; }
;         bf16* SL = (bf16*)C.ST + ((size_t)(seq * 132 + n)) * 4096;
;         if (u + (int)gridDim.x < nunits) HG_FETCH(u + (int)gridDim.x);
;         __syncthreads();
;         LAS fv2* qt2 = (LAS fv2*)qt;
;         qt2[(dir * 8 + e8) * 32 + kp] = (fv2){bl0, bl1};
;         __syncthreads();
	v_cmp_gt_f32_e32 vcc, s78, v11
	v_sub_f32_e32 v18, v13, v16
	s_nop 0
	v_cndmask_b32_e64 v13, 0, 32, vcc
	v_ldexp_f32 v13, v11, v13
	v_log_f32_e32 v13, v13
	v_lshlrev_b32_e32 v11, 16, v10
	v_mul_f32_e32 v11, 0xbfb8aa3b, v11
	v_exp_f32_e32 v11, v11
	v_mul_f32_e32 v16, 0x3f317217, v13
	v_fma_f32 v16, v13, s91, -v16
	v_fmac_f32_e32 v16, 0x3377d1cf, v13
	v_fmac_f32_e32 v16, 0x3f317217, v13
	v_cmp_lt_f32_e64 s[54:55], |v13|, s80
	v_add_f32_e32 v11, 1.0, v11
	v_and_b32_e32 v10, 0xffff0000, v10
	v_cndmask_b32_e64 v13, v13, v16, s[54:55]
	v_cndmask_b32_e32 v16, 0, v249, vcc
	v_div_scale_f32 v12, s[54:55], v11, v11, 1.0
	v_sub_f32_e32 v19, v13, v16
	v_rcp_f32_e32 v13, v12
	v_mul_f32_e32 v10, 0xbfb8aa3b, v10
	v_exp_f32_e32 v10, v10
	v_fma_f32 v16, -v12, v13, 1.0
	v_fmac_f32_e32 v13, v16, v13
	v_div_scale_f32 v16, vcc, 1.0, v11, 1.0
	v_mul_f32_e32 v17, v16, v13
	v_fma_f32 v121, -v12, v17, v16
	v_fmac_f32_e32 v17, v121, v13
	v_fma_f32 v12, -v12, v17, v16
	v_div_fmas_f32 v12, v12, v13, v17
	v_div_fixup_f32 v11, v12, v11, 1.0
	v_fma_f32 v11, v11, v112, v0
	v_add_f32_e32 v10, 1.0, v10
	v_max_f32_e32 v121, 0xda24260, v11
	v_div_scale_f32 v11, s[54:55], v10, v10, 1.0
	v_rcp_f32_e32 v12, v11
	s_nop 0
	v_fma_f32 v13, -v11, v12, 1.0
	v_fmac_f32_e32 v12, v13, v12
	v_div_scale_f32 v13, vcc, 1.0, v10, 1.0
	v_mul_f32_e32 v16, v13, v12
	v_fma_f32 v17, -v11, v16, v13
	v_fmac_f32_e32 v16, v17, v12
	v_fma_f32 v11, -v11, v16, v13
	v_div_fmas_f32 v11, v11, v12, v16
	v_div_fixup_f32 v10, v11, v10, 1.0
	v_fma_f32 v10, v10, v111, v1
	v_cmp_gt_f32_e32 vcc, s78, v121
	v_max_f32_e32 v124, 0xda24260, v10
	v_pk_add_f32 v[16:17], v[2:3], 0 op_sel_hi:[1,0]
	v_cndmask_b32_e64 v10, 0, 32, vcc
	v_ldexp_f32 v10, v121, v10
	v_log_f32_e32 v10, v10
	v_pk_add_f32 v[12:13], v[4:5], v[16:17]
	v_mul_f32_e32 v11, 0x3f317217, v10
	v_fma_f32 v11, v10, s91, -v11
	v_fmac_f32_e32 v11, 0x3377d1cf, v10
	v_fmac_f32_e32 v11, 0x3f317217, v10
	v_cmp_lt_f32_e64 s[54:55], |v10|, s80
	s_nop 1
	v_cndmask_b32_e64 v10, v10, v11, s[54:55]
	v_cndmask_b32_e32 v11, 0, v249, vcc
	v_cmp_gt_f32_e32 vcc, s78, v124
	v_sub_f32_e32 v122, v10, v11
	s_nop 0
	v_cndmask_b32_e64 v10, 0, 32, vcc
	v_ldexp_f32 v10, v124, v10
	v_log_f32_e32 v10, v10
	s_nop 0
	v_mul_f32_e32 v11, 0x3f317217, v10
	v_fma_f32 v11, v10, s91, -v11
	v_fmac_f32_e32 v11, 0x3377d1cf, v10
	v_fmac_f32_e32 v11, 0x3f317217, v10
	v_cmp_lt_f32_e64 s[54:55], |v10|, s80
	s_nop 1
	v_cndmask_b32_e64 v10, v10, v11, s[54:55]
	v_cndmask_b32_e32 v11, 0, v249, vcc
	v_sub_f32_e32 v123, v10, v11
	v_pk_add_f32 v[10:11], v[6:7], v[12:13]
	s_nop 0
	v_pk_add_f32 v[8:9], v[8:9], v[10:11]
	s_nop 0
	v_pk_add_f32 v[6:7], v[14:15], v[8:9]
	v_sub_f32_e32 v15, 1.0, v121
	v_pk_add_f32 v[4:5], v[18:19], v[6:7]
	v_lshlrev_b32_e32 v18, 16, v106
	v_mul_f32_e32 v18, 0xbfb8aa3b, v18
	v_exp_f32_e32 v18, v18
	v_and_b32_e32 v19, 0xffff0000, v106
	v_pk_add_f32 v[2:3], v[122:123], v[4:5]
	v_sub_f32_e32 v14, 1.0, v124
	v_add_f32_e32 v18, 1.0, v18
	v_div_scale_f32 v106, s[54:55], v18, v18, 1.0
	v_rcp_f32_e32 v121, v106
	s_nop 0
	v_fma_f32 v122, -v106, v121, 1.0
	v_fmac_f32_e32 v121, v122, v121
	v_div_scale_f32 v122, vcc, 1.0, v18, 1.0
	v_mul_f32_e32 v123, v122, v121
	v_fma_f32 v124, -v106, v123, v122
	v_fmac_f32_e32 v123, v124, v121
	v_fma_f32 v106, -v106, v123, v122
	v_div_fmas_f32 v106, v106, v121, v123
	v_div_fixup_f32 v18, v106, v18, 1.0
	v_fma_f32 v0, v18, v112, v0
	v_max_f32_e32 v18, 0xda24260, v0
	v_mul_f32_e32 v0, 0xbfb8aa3b, v19
	v_exp_f32_e32 v0, v0
	s_nop 0
	v_add_f32_e32 v0, 1.0, v0
	v_div_scale_f32 v19, s[54:55], v0, v0, 1.0
	v_rcp_f32_e32 v106, v19
	s_nop 0
	v_fma_f32 v112, -v19, v106, 1.0
	v_fmac_f32_e32 v106, v112, v106
	v_div_scale_f32 v112, vcc, 1.0, v0, 1.0
	v_mul_f32_e32 v121, v112, v106
	v_fma_f32 v122, -v19, v121, v112
	v_fmac_f32_e32 v121, v122, v106
	v_fma_f32 v19, -v19, v121, v112
	v_div_fmas_f32 v19, v19, v106, v121
	v_div_fixup_f32 v0, v19, v0, 1.0
	v_cmp_gt_f32_e32 vcc, s78, v18
	v_fmac_f32_e32 v1, v0, v111
	v_max_f32_e32 v106, 0xda24260, v1
	v_cndmask_b32_e64 v0, 0, 32, vcc
	v_ldexp_f32 v0, v18, v0
	v_log_f32_e32 v0, v0
	s_nop 0
	v_mul_f32_e32 v1, 0x3f317217, v0
	v_fma_f32 v1, v0, s91, -v1
	v_fmac_f32_e32 v1, 0x3377d1cf, v0
	v_fmac_f32_e32 v1, 0x3f317217, v0
	v_cmp_lt_f32_e64 s[54:55], |v0|, s80
	s_nop 1
	v_cndmask_b32_e64 v0, v0, v1, s[54:55]
	v_cndmask_b32_e32 v1, 0, v249, vcc
	v_cmp_gt_f32_e32 vcc, s78, v106
	v_sub_f32_e32 v0, v0, v1
	s_nop 0
	v_cndmask_b32_e64 v1, 0, 32, vcc
	v_ldexp_f32 v1, v106, v1
	v_log_f32_e32 v1, v1
	s_nop 0
	v_mul_f32_e32 v19, 0x3f317217, v1
	v_fma_f32 v19, v1, s91, -v19
	v_fmac_f32_e32 v19, 0x3377d1cf, v1
	v_fmac_f32_e32 v19, 0x3f317217, v1
	v_cmp_lt_f32_e64 s[54:55], |v1|, s80
	s_nop 1
	v_cndmask_b32_e64 v1, v1, v19, s[54:55]
	v_cndmask_b32_e32 v19, 0, v249, vcc
	v_sub_f32_e32 v1, v1, v19
	v_pk_add_f32 v[0:1], v[0:1], v[2:3]
	ds_write_b64 v67, v[0:1]
	s_waitcnt lgkmcnt(0)
	s_barrier
; #define LAS __attribute__((address_space(3)))
; DI unsigned pk2(float lo, float hi) { return f2bf(lo) | (f2bf(hi) << 16); }
; template <int MODE> DI void hgrn_chunk_phase(const Args& A, int wave_s, int l, bool need_ctx, LAS unsigned char* lds) {
;     ...
;         float off0 = 0.f, off1 = 0.f, bref0 = 0.f, bref1 = 0.f, bend0 = 0.f, bend1 = 0.f;
; #pragma unroll
;         for (int j = 0; j < 8; ++j) { const fv2 tq = qt2[(dir * 8 + j) * 32 + kp];
;             if (j < e8) { off0 += tq.x; off1 += tq.y; }
;             if (j < 4) { bref0 += tq.x; bref1 += tq.y; }
;             bend0 += tq.x; bend1 += tq.y; }
; #pragma unroll
;         for (int ii = 0; ii < 8; ++ii) { const int i = e8 * 8 + ii; const float bi0 = off0 + cum0[ii], bi1 = off1 + cum1[ii];
;             if (MODE == 0) {
;                 *(LAS unsigned*)(img + i * KV_PITCH + kp * 4) = pk2(kk0[ii] * __expf(bend0 - bi0), kk1[ii] * __expf(bend1 - bi1));
;                 *(LAS unsigned*)(img + HG_IMG + i * KV_PITCH + kp * 4) = vraw[ii];
;             } else {
;                 const float q0 = __builtin_bit_cast(float, qraw[ii] << 16), q1 = __builtin_bit_cast(float, qraw[ii] & 0xffff0000u);
;                 *(LAS unsigned*)(img + i * KV_PITCH + kp * 4) = pk2(q0 * __expf(fminf(bi0 - bref0, 80.f)), q1 * __expf(fminf(bi1 - bref1, 80.f)));
;                 *(LAS unsigned*)(img + HG_IMG + i * KV_PITCH + kp * 4) = pk2(kk0[ii] * __expf(fminf(bref0 - bi0, 80.f)), kk1[ii] * __expf(fminf(bref1 - bi1, 80.f)));
;                 *(LAS unsigned*)(img + 2 * HG_IMG + i * KV_PITCH + kp * 4) = pk2(q0 * __expf(bi0), q1 * __expf(bi1));
;                 *(LAS unsigned*)(img + 3 * HG_IMG + i * KV_PITCH + kp * 4) = vraw[ii];
;             }
	ds_read2_b64 v[122:125], v60 offset1:32
	v_sub_f32_e32 v19, 1.0, v18
	v_sub_f32_e32 v18, 1.0, v106
	s_andn2_b64 vcc, exec, s[36:37]
	s_waitcnt lgkmcnt(0)
	v_add_f32_e32 v106, 0, v122
	v_add_f32_e32 v111, 0, v123
	v_cndmask_b32_e64 v112, 0, v111, s[52:53]
	v_cndmask_b32_e64 v121, 0, v106, s[52:53]
	v_add_f32_e32 v122, v124, v121
	v_add_f32_e32 v123, v125, v112
	v_cndmask_b32_e64 v112, v112, v123, s[4:5]
	v_cndmask_b32_e64 v121, v121, v122, s[4:5]
	v_add_f32_e32 v106, v106, v124
	v_add_f32_e32 v111, v111, v125
	ds_read2_b64 v[122:125], v60 offset0:64 offset1:96
	s_waitcnt lgkmcnt(0)
	v_add_f32_e32 v126, v122, v121
	v_add_f32_e32 v127, v123, v112
	v_cndmask_b32_e64 v112, v112, v127, s[6:7]
	v_cndmask_b32_e64 v121, v121, v126, s[6:7]
	v_add_f32_e32 v106, v106, v122
	v_add_f32_e32 v122, v111, v123
	v_add_f32_e32 v111, v124, v121
	v_add_f32_e32 v123, v125, v112
	v_cndmask_b32_e64 v112, v112, v123, s[8:9]
	v_cndmask_b32_e64 v121, v121, v111, s[8:9]
	v_add_f32_e32 v111, v106, v124
	v_add_f32_e32 v106, v122, v125
	ds_read2_b64 v[122:125], v60 offset0:128 offset1:160
	s_waitcnt lgkmcnt(0)
	v_add_f32_e32 v122, v122, v121
	v_add_f32_e32 v123, v123, v112
	v_cndmask_b32_e64 v112, v112, v123, s[10:11]
	v_cndmask_b32_e64 v121, v121, v122, s[10:11]
	v_add_f32_e32 v122, v124, v121
	v_add_f32_e32 v123, v125, v112
	v_cndmask_b32_e64 v112, v112, v123, s[12:13]
	v_cndmask_b32_e64 v121, v121, v122, s[12:13]
	ds_read2_b64 v[122:125], v60 offset0:192 offset1:224
	s_waitcnt lgkmcnt(0)
	v_add_f32_e32 v122, v122, v121
	v_add_f32_e32 v123, v123, v112
	v_cndmask_b32_e64 v121, v121, v122, s[14:15]
	v_cndmask_b32_e64 v112, v112, v123, s[14:15]
	v_add_f32_e32 v122, v124, v121
	v_add_f32_e32 v123, v125, v112
	v_cndmask_b32_e64 v121, v121, v122, s[16:17]
	v_cndmask_b32_e64 v112, v112, v123, s[16:17]
	v_add_f32_e32 v16, v16, v121
	v_add_f32_e32 v17, v17, v112
	v_sub_f32_e32 v123, v16, v111
	v_min_f32_e32 v123, 0x42a00000, v123
	v_sub_f32_e32 v124, v17, v106
	v_mul_f32_e32 v123, 0x3fb8aa3b, v123
	v_min_f32_e32 v124, 0x42a00000, v124
	v_exp_f32_e32 v123, v123
	v_mul_f32_e32 v124, 0x3fb8aa3b, v124
	v_exp_f32_e32 v124, v124
	v_lshlrev_b32_e32 v122, 16, v43
	v_and_b32_e32 v43, 0xffff0000, v43
	v_mul_f32_e32 v123, v123, v122
	v_mul_f32_e32 v124, v124, v43
	v_bfe_u32 v125, v123, 16, 1
	v_add3_u32 v123, v123, v125, s79
	v_bfe_u32 v125, v124, 16, 1
	v_lshrrev_b32_e32 v123, 16, v123
	v_add3_u32 v124, v124, v125, s79
	v_and_or_b32 v123, v124, s82, v123
	v_sub_f32_e32 v124, v111, v16
	v_min_f32_e32 v124, 0x42a00000, v124
	v_mul_f32_e32 v124, 0x3fb8aa3b, v124
	v_exp_f32_e32 v124, v124
	v_mul_f32_e32 v16, 0x3fb8aa3b, v16
	v_exp_f32_e32 v16, v16
	v_add_f32_e32 v12, v12, v121
	v_mul_f32_e32 v108, v108, v124
	v_sub_f32_e32 v124, v106, v17
	v_mul_f32_e32 v17, 0x3fb8aa3b, v17
	v_exp_f32_e32 v17, v17
	v_mul_f32_e32 v16, v16, v122
	v_add_f32_e32 v13, v13, v112
	v_min_f32_e32 v124, 0x42a00000, v124
	v_mul_f32_e32 v17, v17, v43
	v_bfe_u32 v43, v16, 16, 1
	v_add3_u32 v16, v16, v43, s79
	v_bfe_u32 v43, v17, 16, 1
	v_lshrrev_b32_e32 v16, 16, v16
	v_add3_u32 v17, v17, v43, s79
	v_and_or_b32 v16, v17, s82, v16
	ds_write2st64_b32 v68, v16, v42 offset0:72 offset1:108
	v_lshlrev_b32_e32 v16, 16, v41
	v_and_b32_e32 v17, 0xffff0000, v41
	v_sub_f32_e32 v41, v12, v111
	v_min_f32_e32 v41, 0x42a00000, v41
	v_sub_f32_e32 v42, v13, v106
	v_mul_f32_e32 v41, 0x3fb8aa3b, v41
	v_min_f32_e32 v42, 0x42a00000, v42
	v_exp_f32_e32 v41, v41
	v_mul_f32_e32 v42, 0x3fb8aa3b, v42
	v_exp_f32_e32 v42, v42
	v_mul_f32_e32 v124, 0x3fb8aa3b, v124
	v_mul_f32_e32 v41, v41, v16
	v_bfe_u32 v43, v41, 16, 1
	v_mul_f32_e32 v42, v42, v17
	v_add3_u32 v41, v41, v43, s79
	v_bfe_u32 v43, v42, 16, 1
	v_lshrrev_b32_e32 v41, 16, v41
	v_add3_u32 v42, v42, v43, s79
	v_and_or_b32 v41, v42, s82, v41
	v_sub_f32_e32 v42, v111, v12
	v_mul_f32_e32 v12, 0x3fb8aa3b, v12
	v_sub_f32_e32 v43, v106, v13
	v_exp_f32_e32 v12, v12
	v_mul_f32_e32 v13, 0x3fb8aa3b, v13
	v_exp_f32_e32 v13, v13
	v_exp_f32_e32 v124, v124
	v_mul_f32_e32 v12, v12, v16
	v_min_f32_e32 v42, 0x42a00000, v42
	v_mul_f32_e32 v13, v13, v17
	v_bfe_u32 v16, v12, 16, 1
	v_mul_f32_e32 v42, 0x3fb8aa3b, v42
	v_min_f32_e32 v43, 0x42a00000, v43
	v_add3_u32 v12, v12, v16, s79
	v_bfe_u32 v16, v13, 16, 1
	v_add_f32_e32 v10, v10, v121
	v_exp_f32_e32 v42, v42
	v_mul_f32_e32 v43, 0x3fb8aa3b, v43
	v_lshrrev_b32_e32 v12, 16, v12
	v_add3_u32 v13, v13, v16, s79
	v_add_f32_e32 v11, v11, v112
	v_sub_f32_e32 v17, v10, v111
	v_mul_f32_e32 v107, v107, v124
	v_bfe_u32 v124, v108, 16, 1
	v_exp_f32_e32 v43, v43
	v_and_or_b32 v12, v13, s82, v12
	v_lshlrev_b32_e32 v13, 16, v40
	v_and_b32_e32 v16, 0xffff0000, v40
	v_min_f32_e32 v17, 0x42a00000, v17
	v_sub_f32_e32 v40, v11, v106
	v_add3_u32 v108, v108, v124, s79
	v_bfe_u32 v124, v107, 16, 1
	v_mul_f32_e32 v17, 0x3fb8aa3b, v17
	v_min_f32_e32 v40, 0x42a00000, v40
	v_lshrrev_b32_e32 v108, 16, v108
	v_add3_u32 v107, v107, v124, s79
	v_exp_f32_e32 v17, v17
	v_mul_f32_e32 v40, 0x3fb8aa3b, v40
	v_and_or_b32 v107, v107, s82, v108
	v_mul_f32_e32 v42, v110, v42
	v_exp_f32_e32 v40, v40
	ds_write2st64_b32 v68, v123, v107 offset1:36
	v_mul_f32_e32 v43, v109, v43
	v_bfe_u32 v107, v42, 16, 1
	v_add3_u32 v42, v42, v107, s79
	v_bfe_u32 v107, v43, 16, 1
	v_lshrrev_b32_e32 v42, 16, v42
	v_add3_u32 v43, v43, v107, s79
	v_mul_f32_e32 v17, v17, v13
	v_and_or_b32 v42, v43, s82, v42
	v_mul_f32_e32 v40, v40, v16
	v_bfe_u32 v43, v17, 16, 1
	v_add3_u32 v17, v17, v43, s79
	v_bfe_u32 v43, v40, 16, 1
	v_lshrrev_b32_e32 v17, 16, v17
	v_add3_u32 v40, v40, v43, s79
	v_and_or_b32 v17, v40, s82, v17
	ds_write2_b32 v69, v41, v17 offset1:36
	v_sub_f32_e32 v17, v111, v10
	v_min_f32_e32 v17, 0x42a00000, v17
; #define LAS __attribute__((address_space(3)))
; DI unsigned pk2(float lo, float hi) { return f2bf(lo) | (f2bf(hi) << 16); }
; template <int MODE> DI void hgrn_chunk_phase(const Args& A, int wave_s, int l, bool need_ctx, LAS unsigned char* lds) {
;     ...
;         for (int ii = 0; ii < 8; ++ii) { const int i = e8 * 8 + ii; const float bi0 = off0 + cum0[ii], bi1 = off1 + cum1[ii];
;             if (MODE == 0) {
;                 *(LAS unsigned*)(img + i * KV_PITCH + kp * 4) = pk2(kk0[ii] * __expf(bend0 - bi0), kk1[ii] * __expf(bend1 - bi1));
;                 *(LAS unsigned*)(img + HG_IMG + i * KV_PITCH + kp * 4) = vraw[ii];
;             } else {
;                 const float q0 = __builtin_bit_cast(float, qraw[ii] << 16), q1 = __builtin_bit_cast(float, qraw[ii] & 0xffff0000u);
;                 *(LAS unsigned*)(img + i * KV_PITCH + kp * 4) = pk2(q0 * __expf(fminf(bi0 - bref0, 80.f)), q1 * __expf(fminf(bi1 - bref1, 80.f)));
;                 *(LAS unsigned*)(img + HG_IMG + i * KV_PITCH + kp * 4) = pk2(kk0[ii] * __expf(fminf(bref0 - bi0, 80.f)), kk1[ii] * __expf(fminf(bref1 - bi1, 80.f)));
;                 *(LAS unsigned*)(img + 2 * HG_IMG + i * KV_PITCH + kp * 4) = pk2(q0 * __expf(bi0), q1 * __expf(bi1));
;                 *(LAS unsigned*)(img + 3 * HG_IMG + i * KV_PITCH + kp * 4) = vraw[ii];
;             }
	v_sub_f32_e32 v40, v106, v11
	v_mul_f32_e32 v17, 0x3fb8aa3b, v17
	v_min_f32_e32 v40, 0x42a00000, v40
	v_exp_f32_e32 v17, v17
	v_mul_f32_e32 v40, 0x3fb8aa3b, v40
	v_exp_f32_e32 v40, v40
	v_mul_f32_e32 v11, 0x3fb8aa3b, v11
	v_mul_f32_e32 v17, v114, v17
	v_mul_f32_e32 v10, 0x3fb8aa3b, v10
	v_exp_f32_e32 v11, v11
	v_mul_f32_e32 v40, v113, v40
	v_bfe_u32 v41, v17, 16, 1
	v_exp_f32_e32 v10, v10
	v_add3_u32 v17, v17, v41, s79
	v_bfe_u32 v41, v40, 16, 1
	v_lshrrev_b32_e32 v17, 16, v17
	v_add3_u32 v40, v40, v41, s79
	v_add_f32_e32 v8, v8, v121
	v_and_or_b32 v17, v40, s82, v17
	v_add_u32_e32 v40, 0x2400, v69
	v_mul_f32_e32 v11, v11, v16
	v_add_f32_e32 v9, v9, v112
	v_sub_f32_e32 v16, v8, v111
	ds_write2_b32 v40, v42, v17 offset1:36
	v_mul_f32_e32 v10, v10, v13
	v_min_f32_e32 v16, 0x42a00000, v16
	v_sub_f32_e32 v17, v9, v106
	v_bfe_u32 v13, v10, 16, 1
	v_mul_f32_e32 v16, 0x3fb8aa3b, v16
	v_min_f32_e32 v17, 0x42a00000, v17
	v_add3_u32 v10, v10, v13, s79
	v_bfe_u32 v13, v11, 16, 1
	v_exp_f32_e32 v16, v16
	v_mul_f32_e32 v17, 0x3fb8aa3b, v17
	v_lshrrev_b32_e32 v10, 16, v10
	v_add3_u32 v11, v11, v13, s79
	v_exp_f32_e32 v17, v17
	v_and_or_b32 v10, v11, s82, v10
	v_add_u32_e32 v11, 0x4800, v69
	ds_write2_b32 v11, v12, v10 offset1:36
	v_lshlrev_b32_e32 v12, 16, v37
	v_and_b32_e32 v13, 0xffff0000, v37
	v_mul_f32_e32 v16, v16, v12
	v_mul_f32_e32 v17, v17, v13
	v_bfe_u32 v37, v16, 16, 1
	v_add3_u32 v16, v16, v37, s79
	v_bfe_u32 v37, v17, 16, 1
	v_lshrrev_b32_e32 v16, 16, v16
	v_add3_u32 v17, v17, v37, s79
	v_and_or_b32 v16, v17, s82, v16
	v_sub_f32_e32 v17, v111, v8
	v_mul_f32_e32 v8, 0x3fb8aa3b, v8
	v_sub_f32_e32 v37, v106, v9
	v_exp_f32_e32 v8, v8
	v_mul_f32_e32 v9, 0x3fb8aa3b, v9
	v_exp_f32_e32 v9, v9
	v_min_f32_e32 v17, 0x42a00000, v17
	v_mul_f32_e32 v8, v8, v12
	v_bfe_u32 v12, v8, 16, 1
	v_mul_f32_e32 v9, v9, v13
	v_mul_f32_e32 v17, 0x3fb8aa3b, v17
	v_min_f32_e32 v37, 0x42a00000, v37
	v_add3_u32 v8, v8, v12, s79
	v_bfe_u32 v12, v9, 16, 1
	v_add_f32_e32 v6, v6, v121
	v_exp_f32_e32 v17, v17
	v_mul_f32_e32 v37, 0x3fb8aa3b, v37
	v_lshrrev_b32_e32 v8, 16, v8
	v_add3_u32 v9, v9, v12, s79
	v_add_f32_e32 v7, v7, v112
	v_sub_f32_e32 v13, v6, v111
	v_exp_f32_e32 v37, v37
	v_and_or_b32 v8, v9, s82, v8
	v_lshlrev_b32_e32 v9, 16, v36
	v_and_b32_e32 v12, 0xffff0000, v36
	v_min_f32_e32 v13, 0x42a00000, v13
	v_sub_f32_e32 v36, v7, v106
	v_mul_f32_e32 v13, 0x3fb8aa3b, v13
	v_min_f32_e32 v36, 0x42a00000, v36
	v_exp_f32_e32 v13, v13
	v_mul_f32_e32 v36, 0x3fb8aa3b, v36
	v_add_u32_e32 v10, 0x6c00, v69
	v_mul_f32_e32 v17, v116, v17
	v_exp_f32_e32 v36, v36
	ds_write2_b32 v10, v39, v38 offset1:36
	v_mul_f32_e32 v37, v115, v37
	v_bfe_u32 v38, v17, 16, 1
	v_add3_u32 v17, v17, v38, s79
	v_bfe_u32 v38, v37, 16, 1
	v_lshrrev_b32_e32 v17, 16, v17
	v_add3_u32 v37, v37, v38, s79
	v_mul_f32_e32 v13, v13, v9
	v_and_or_b32 v17, v37, s82, v17
	v_mul_f32_e32 v36, v36, v12
	v_bfe_u32 v37, v13, 16, 1
	v_add3_u32 v13, v13, v37, s79
	v_bfe_u32 v37, v36, 16, 1
	v_lshrrev_b32_e32 v13, 16, v13
	v_add3_u32 v36, v36, v37, s79
	v_and_or_b32 v13, v36, s82, v13
	ds_write2_b32 v69, v16, v13 offset0:72 offset1:108
	v_sub_f32_e32 v13, v111, v6
	v_min_f32_e32 v13, 0x42a00000, v13
	v_sub_f32_e32 v16, v106, v7
	v_mul_f32_e32 v13, 0x3fb8aa3b, v13
	v_min_f32_e32 v16, 0x42a00000, v16
	v_mul_f32_e32 v6, 0x3fb8aa3b, v6
	v_exp_f32_e32 v13, v13
	v_mul_f32_e32 v16, 0x3fb8aa3b, v16
	v_exp_f32_e32 v6, v6
	v_mul_f32_e32 v7, 0x3fb8aa3b, v7
	v_exp_f32_e32 v16, v16
	v_exp_f32_e32 v7, v7
	v_mul_f32_e32 v13, v118, v13
	v_mul_f32_e32 v6, v6, v9
	v_mul_f32_e32 v16, v117, v16
	v_bfe_u32 v36, v13, 16, 1
	v_mul_f32_e32 v7, v7, v12
	v_bfe_u32 v9, v6, 16, 1
	v_add3_u32 v13, v13, v36, s79
	v_bfe_u32 v36, v16, 16, 1
	v_add3_u32 v6, v6, v9, s79
	v_bfe_u32 v9, v7, 16, 1
	v_lshrrev_b32_e32 v13, 16, v13
	v_add3_u32 v16, v16, v36, s79
	v_lshrrev_b32_e32 v6, 16, v6
	v_add3_u32 v7, v7, v9, s79
	v_and_or_b32 v13, v16, s82, v13
	v_and_or_b32 v6, v7, s82, v6
	v_add_f32_e32 v4, v4, v121
	ds_write2_b32 v40, v17, v13 offset0:72 offset1:108
	ds_write2_b32 v11, v8, v6 offset0:72 offset1:108
	ds_write2_b32 v10, v35, v34 offset0:72 offset1:108
	v_add_f32_e32 v5, v5, v112
	v_sub_f32_e32 v8, v4, v111
	v_min_f32_e32 v8, 0x42a00000, v8
	v_sub_f32_e32 v9, v5, v106
	v_mul_f32_e32 v8, 0x3fb8aa3b, v8
	v_min_f32_e32 v9, 0x42a00000, v9
	v_exp_f32_e32 v8, v8
	v_mul_f32_e32 v9, 0x3fb8aa3b, v9
	v_exp_f32_e32 v9, v9
	v_lshlrev_b32_e32 v6, 16, v33
	v_and_b32_e32 v7, 0xffff0000, v33
	v_mul_f32_e32 v8, v8, v6
	v_mul_f32_e32 v9, v9, v7
	v_bfe_u32 v12, v8, 16, 1
	v_add3_u32 v8, v8, v12, s79
	v_bfe_u32 v12, v9, 16, 1
	v_lshrrev_b32_e32 v8, 16, v8
	v_add3_u32 v9, v9, v12, s79
	v_and_or_b32 v8, v9, s82, v8
	v_sub_f32_e32 v9, v111, v4
	v_min_f32_e32 v9, 0x42a00000, v9
	v_sub_f32_e32 v12, v106, v5
	v_mul_f32_e32 v9, 0x3fb8aa3b, v9
	v_min_f32_e32 v12, 0x42a00000, v12
	v_exp_f32_e32 v9, v9
	v_mul_f32_e32 v12, 0x3fb8aa3b, v12
	v_exp_f32_e32 v12, v12
	v_mul_f32_e32 v5, 0x3fb8aa3b, v5
	v_exp_f32_e32 v5, v5
	v_mul_f32_e32 v9, v120, v9
	v_mul_f32_e32 v4, 0x3fb8aa3b, v4
	v_mul_f32_e32 v12, v119, v12
	v_bfe_u32 v13, v9, 16, 1
	v_exp_f32_e32 v4, v4
	v_add3_u32 v9, v9, v13, s79
	v_bfe_u32 v13, v12, 16, 1
	v_add_f32_e32 v2, v2, v121
	v_lshrrev_b32_e32 v9, 16, v9
; #define LAS __attribute__((address_space(3)))
; DI unsigned f2bf(float f) { unsigned u = __builtin_bit_cast(unsigned, f); return (u + 0x7fffu + ((u >> 16) & 1u)) >> 16; }
; template <int MODE> DI void hgrn_chunk_phase(const Args& A, int wave_s, int l, bool need_ctx, LAS unsigned char* lds) {
;     ...
;         for (int ii = 0; ii < 8; ++ii) { const int i = e8 * 8 + ii; const float bi0 = off0 + cum0[ii], bi1 = off1 + cum1[ii];
;             if (MODE == 0) {
;                 *(LAS unsigned*)(img + i * KV_PITCH + kp * 4) = pk2(kk0[ii] * __expf(bend0 - bi0), kk1[ii] * __expf(bend1 - bi1));
;                 *(LAS unsigned*)(img + HG_IMG + i * KV_PITCH + kp * 4) = vraw[ii];
;             } else {
;                 const float q0 = __builtin_bit_cast(float, qraw[ii] << 16), q1 = __builtin_bit_cast(float, qraw[ii] & 0xffff0000u);
;                 *(LAS unsigned*)(img + i * KV_PITCH + kp * 4) = pk2(q0 * __expf(fminf(bi0 - bref0, 80.f)), q1 * __expf(fminf(bi1 - bref1, 80.f)));
;                 *(LAS unsigned*)(img + HG_IMG + i * KV_PITCH + kp * 4) = pk2(kk0[ii] * __expf(fminf(bref0 - bi0, 80.f)), kk1[ii] * __expf(fminf(bref1 - bi1, 80.f)));
;                 *(LAS unsigned*)(img + 2 * HG_IMG + i * KV_PITCH + kp * 4) = pk2(q0 * __expf(bi0), q1 * __expf(bi1));
;                 *(LAS unsigned*)(img + 3 * HG_IMG + i * KV_PITCH + kp * 4) = vraw[ii];
;             }
;         }
;         if (MODE == 0) { if (e8 == 0) *(fv2*)(DEC + (seq * 132 + n) * 64 + 2 * kp) = (fv2){__expf(bend0), __expf(bend1)}; }
;         else {
; #pragma unroll
;             for (int ii = 0; ii < 8; ++ii) { const int k = e8 * 8 + ii; *(LAS unsigned*)(img + 4 * HG_IMG + k * KV_PITCH + kp * 4) = spv[ii]; }
;         }
;         __syncthreads();
;         if (MODE == 0) {
;             const int kblk = (wave >> 1) & 1, dvblk = wave & 1;
;             f32x16 S;
; #pragma unroll
;             for (int i = 0; i < 16; ++i) S[i] = 0.f;
; #pragma unroll
;             for (int is = 0; is < 4; ++is) { const bf16x8 a = tr_nat(img, 16 * is, 32 * kblk, lane), bb = tr_nat(img + HG_IMG, 16 * is, 32 * dvblk, lane); S = MFMA32(a, bb, S); }
; #pragma unroll
;             for (int i = 0; i < 16; ++i) { const int k = 32 * kblk + (i & 3) + 8 * (i >> 2) + 4 * h5; SL[k * 64 + 32 * dvblk + r] = (bf16)f2bf(S[i]); }
;         } else {
;             const int tblk = (wave >> 1) & 1, mt = wave & 1;
	v_add3_u32 v12, v12, v13, s79
	v_mul_f32_e32 v5, v5, v7
	v_add_f32_e32 v3, v3, v112
	v_sub_f32_e32 v7, v2, v111
	v_and_or_b32 v9, v12, s82, v9
	v_min_f32_e32 v7, 0x42a00000, v7
	v_sub_f32_e32 v12, v3, v106
	v_mul_f32_e32 v4, v4, v6
	v_mul_f32_e32 v7, 0x3fb8aa3b, v7
	v_min_f32_e32 v12, 0x42a00000, v12
	v_bfe_u32 v6, v4, 16, 1
	v_exp_f32_e32 v7, v7
	v_mul_f32_e32 v12, 0x3fb8aa3b, v12
	v_add3_u32 v4, v4, v6, s79
	v_bfe_u32 v6, v5, 16, 1
	v_exp_f32_e32 v12, v12
	v_lshrrev_b32_e32 v4, 16, v4
	v_add3_u32 v5, v5, v6, s79
	v_and_or_b32 v4, v5, s82, v4
	v_lshlrev_b32_e32 v5, 16, v32
	v_and_b32_e32 v6, 0xffff0000, v32
	v_mul_f32_e32 v7, v7, v5
	v_mul_f32_e32 v12, v12, v6
	v_bfe_u32 v13, v7, 16, 1
	v_add3_u32 v7, v7, v13, s79
	v_bfe_u32 v13, v12, 16, 1
	v_lshrrev_b32_e32 v7, 16, v7
	v_add3_u32 v12, v12, v13, s79
	v_and_or_b32 v7, v12, s82, v7
	ds_write2_b32 v69, v8, v7 offset0:144 offset1:180
	v_sub_f32_e32 v7, v111, v2
	v_min_f32_e32 v7, 0x42a00000, v7
	v_sub_f32_e32 v8, v106, v3
	v_mul_f32_e32 v7, 0x3fb8aa3b, v7
	v_min_f32_e32 v8, 0x42a00000, v8
	v_mul_f32_e32 v2, 0x3fb8aa3b, v2
	v_exp_f32_e32 v7, v7
	v_mul_f32_e32 v8, 0x3fb8aa3b, v8
	v_exp_f32_e32 v2, v2
	v_mul_f32_e32 v3, 0x3fb8aa3b, v3
	v_exp_f32_e32 v8, v8
	v_exp_f32_e32 v3, v3
	v_mul_f32_e32 v7, v15, v7
	v_mul_f32_e32 v2, v2, v5
	v_mul_f32_e32 v8, v14, v8
	v_bfe_u32 v12, v7, 16, 1
	v_mul_f32_e32 v3, v3, v6
	v_bfe_u32 v5, v2, 16, 1
	v_add3_u32 v7, v7, v12, s79
	v_bfe_u32 v12, v8, 16, 1
	v_add3_u32 v2, v2, v5, s79
	v_bfe_u32 v5, v3, 16, 1
	v_lshrrev_b32_e32 v7, 16, v7
	v_add3_u32 v8, v8, v12, s79
	v_lshrrev_b32_e32 v2, 16, v2
	v_add3_u32 v3, v3, v5, s79
	v_and_or_b32 v7, v8, s82, v7
	v_and_or_b32 v2, v3, s82, v2
	v_add_f32_e32 v0, v0, v121
	ds_write2_b32 v40, v9, v7 offset0:144 offset1:180
	ds_write2_b32 v11, v4, v2 offset0:144 offset1:180
	ds_write2_b32 v10, v31, v30 offset0:144 offset1:180
	v_add_f32_e32 v1, v1, v112
	v_sub_f32_e32 v4, v0, v111
	v_min_f32_e32 v4, 0x42a00000, v4
	v_sub_f32_e32 v5, v1, v106
	v_mul_f32_e32 v4, 0x3fb8aa3b, v4
	v_min_f32_e32 v5, 0x42a00000, v5
	v_exp_f32_e32 v4, v4
	v_mul_f32_e32 v5, 0x3fb8aa3b, v5
	v_exp_f32_e32 v5, v5
	v_lshlrev_b32_e32 v2, 16, v29
	v_and_b32_e32 v3, 0xffff0000, v29
	v_mul_f32_e32 v4, v4, v2
	v_mul_f32_e32 v5, v5, v3
	v_bfe_u32 v6, v4, 16, 1
	v_add3_u32 v4, v4, v6, s79
	v_bfe_u32 v6, v5, 16, 1
	v_lshrrev_b32_e32 v4, 16, v4
	v_add3_u32 v5, v5, v6, s79
	v_and_or_b32 v4, v5, s82, v4
	ds_write_b32 v69, v4 offset:864
	v_sub_f32_e32 v4, v111, v0
	v_min_f32_e32 v4, 0x42a00000, v4
	v_sub_f32_e32 v5, v106, v1
	v_mul_f32_e32 v4, 0x3fb8aa3b, v4
	v_min_f32_e32 v5, 0x42a00000, v5
	v_mul_f32_e32 v0, 0x3fb8aa3b, v0
	v_exp_f32_e32 v4, v4
	v_mul_f32_e32 v5, 0x3fb8aa3b, v5
	v_exp_f32_e32 v0, v0
	v_mul_f32_e32 v1, 0x3fb8aa3b, v1
	v_exp_f32_e32 v5, v5
	v_exp_f32_e32 v1, v1
	v_mul_f32_e32 v4, v19, v4
	v_mul_f32_e32 v0, v0, v2
	v_mul_f32_e32 v5, v18, v5
	v_bfe_u32 v6, v4, 16, 1
	v_mul_f32_e32 v1, v1, v3
	v_bfe_u32 v2, v0, 16, 1
	v_add3_u32 v4, v4, v6, s79
	v_bfe_u32 v6, v5, 16, 1
	v_add3_u32 v0, v0, v2, s79
	v_bfe_u32 v2, v1, 16, 1
	v_lshrrev_b32_e32 v4, 16, v4
	v_add3_u32 v5, v5, v6, s79
	v_lshrrev_b32_e32 v0, 16, v0
	v_add3_u32 v1, v1, v2, s79
	v_and_or_b32 v4, v5, s82, v4
	v_and_or_b32 v0, v1, s82, v0
	ds_write_b32 v69, v4 offset:10080
	ds_write_b32 v69, v0 offset:19296
	ds_write_b32 v69, v28 offset:28512
	ds_write_b32 v68, v27 offset:36864
	v_add_u32_e32 v0, 0x9000, v69
	ds_write2_b32 v0, v25, v26 offset1:36
	ds_write2_b32 v0, v23, v24 offset0:72 offset1:108
	ds_write2_b32 v0, v21, v22 offset0:144 offset1:180
	ds_write_b32 v69, v20 offset:37728
	s_waitcnt lgkmcnt(0)
	s_barrier
	ds_read_b128 v[16:19], v72
	ds_read_b128 v[36:39], v72 offset:32
	ds_read_b128 v[0:3], v71 offset:9216
	ds_read_b128 v[20:23], v71 offset:9248
	s_waitcnt lgkmcnt(1)
	v_mfma_f32_32x32x16_bf16 v[0:15], v[0:3], v[16:19], 0
	s_waitcnt lgkmcnt(0)
	v_mfma_f32_32x32x16_bf16 v[0:15], v[20:23], v[36:39], v[0:15]
	ds_read_b128 v[20:23], v71 offset:9280
	ds_read_b128 v[40:43], v72 offset:64
	s_waitcnt lgkmcnt(0)
	v_mfma_f32_32x32x16_bf16 v[0:15], v[20:23], v[40:43], v[0:15]
	ds_read_b128 v[20:23], v71 offset:9312
	ds_read_b128 v[32:35], v72 offset:96
	s_waitcnt lgkmcnt(0)
	v_mfma_f32_32x32x16_bf16 v[0:15], v[20:23], v[32:35], v[0:15]
	s_cbranch_vccnz .LBB0_396
	v_readlane_b32 s36, v255, 42
	v_readlane_b32 s37, v255, 43
	s_nop 8
	v_cndmask_b32_e64 v5, v5, 0, s[28:29]
	v_cndmask_b32_e64 v6, v6, 0, s[30:31]
	v_cndmask_b32_e64 v0, v0, 0, s[36:37]
	v_readlane_b32 s36, v255, 44
	v_readlane_b32 s37, v255, 45
	v_cndmask_b32_e64 v7, v7, 0, s[34:35]
	v_cndmask_b32_e64 v8, v8, 0, s[66:67]
	v_cndmask_b32_e64 v1, 0, v1, s[36:37]
	v_readlane_b32 s36, v255, 46
	v_readlane_b32 s37, v255, 47
	v_cndmask_b32_e64 v9, v9, 0, s[68:69]
	v_cndmask_b32_e64 v10, v10, 0, s[70:71]
	v_cndmask_b32_e64 v2, v2, 0, s[36:37]
	v_readlane_b32 s36, v255, 48
	v_readlane_b32 s37, v255, 49
	v_cndmask_b32_e64 v11, v11, 0, s[18:19]
	v_cndmask_b32_e64 v12, v12, 0, s[20:21]
	v_cndmask_b32_e64 v3, v3, 0, s[36:37]
	v_readlane_b32 s36, v255, 50
	v_readlane_b32 s37, v255, 51
	v_cndmask_b32_e64 v13, v13, 0, s[22:23]
	v_cndmask_b32_e64 v14, v14, 0, s[24:25]
	v_cndmask_b32_e64 v4, v4, 0, s[36:37]
	v_cndmask_b32_e64 v15, v15, 0, s[26:27]
